# weight conversion: the 32 folded-gain loads of an item issued up front instead of one serialized round trip each
# baseline (speedup 1.0000x reference)
.LBB0_626:
	s_andn2_b64 vcc, exec, s[0:1]
	s_cbranch_vccnz .LBB0_708
	v_mov_b32_e32 v27, 0x204c0
	s_add_i32 s16, s78, 0xffffd100
	v_add_u32_e32 v27, 0, v27
	ds_read2_b32 v[28:29], v27 offset1:1
	v_mov_b32_e32 v27, 0x204b0
	v_lshlrev_b32_e32 v96, 2, v0
	v_add_u32_e32 v27, 0, v27
	s_waitcnt lgkmcnt(0)
	v_readfirstlane_b32 s0, v28
	v_readfirstlane_b32 s1, v29
	ds_read2_b32 v[28:29], v27 offset1:1
	s_add_u32 s2, s0, s4
	s_addc_u32 s8, s1, s5
	s_lshl_b64 s[14:15], s[60:61], 2
	s_waitcnt lgkmcnt(0)
	v_readfirstlane_b32 s0, v28
	v_readfirstlane_b32 s1, v29
	s_add_u32 s58, s0, s14
	s_addc_u32 s59, s1, s15
	s_lshl_b32 s14, s16, 6
	s_lshl_b32 s15, s16, 3
	s_and_b32 s14, s14, 0xc0
	s_and_b32 s18, s15, 32
	s_or_b32 s14, s14, s18
	s_and_b32 s18, s15, 0x3c0
	s_lshl_b32 s14, s14, 2
	s_add_u32 s14, s2, s14
	v_or_b32_e32 v29, s18, v2
	s_addc_u32 s15, s8, 0
	v_lshl_add_u64 v[30:31], s[14:15], 0, v[96:97]
	v_lshlrev_b32_e32 v96, 10, v29
	v_lshl_add_u64 v[62:63], v[30:31], 0, v[96:97]
	s_movk_i32 s2, 0x1000
	v_add_co_u32_e32 v30, vcc, s2, v62
	flat_load_dword v59, v[62:63]
	flat_load_dword v60, v[62:63] offset:2048
	v_addc_co_u32_e32 v31, vcc, 0, v63, vcc
	flat_load_dword v57, v[30:31]
	flat_load_dword v58, v[30:31] offset:2048
	v_add_co_u32_e32 v30, vcc, s96, v62
	s_movk_i32 s2, 0x3000
	s_nop 0
	v_addc_co_u32_e32 v31, vcc, 0, v63, vcc
	flat_load_dword v55, v[30:31]
	flat_load_dword v56, v[30:31] offset:2048
	v_add_co_u32_e32 v30, vcc, s2, v62
	s_movk_i32 s2, 0x4000
	s_nop 0
	v_addc_co_u32_e32 v31, vcc, 0, v63, vcc
	flat_load_dword v53, v[30:31]
	flat_load_dword v54, v[30:31] offset:2048
	v_add_co_u32_e32 v30, vcc, s2, v62
	s_movk_i32 s2, 0x5000
	s_nop 0
	v_addc_co_u32_e32 v31, vcc, 0, v63, vcc
	flat_load_dword v51, v[30:31]
	flat_load_dword v52, v[30:31] offset:2048
	v_add_co_u32_e32 v30, vcc, s2, v62
	s_movk_i32 s2, 0x6000
	s_nop 0
	v_addc_co_u32_e32 v31, vcc, 0, v63, vcc
	flat_load_dword v49, v[30:31]
	flat_load_dword v50, v[30:31] offset:2048
	v_add_co_u32_e32 v30, vcc, s2, v62
	s_movk_i32 s2, 0x7000
	s_nop 0
	v_addc_co_u32_e32 v31, vcc, 0, v63, vcc
	flat_load_dword v47, v[30:31]
	flat_load_dword v48, v[30:31] offset:2048
	v_add_co_u32_e32 v30, vcc, s2, v62
	s_mov_b32 s2, 0x8000
	s_nop 0
	v_addc_co_u32_e32 v31, vcc, 0, v63, vcc
	flat_load_dword v45, v[30:31]
	flat_load_dword v46, v[30:31] offset:2048
	v_add_co_u32_e32 v30, vcc, s2, v62
	s_mov_b32 s2, 0xa000
	s_nop 0
	v_addc_co_u32_e32 v31, vcc, 0, v63, vcc
	flat_load_dword v43, v[30:31]
	flat_load_dword v44, v[30:31] offset:2048
	v_add_co_u32_e32 v30, vcc, 0x9000, v62
	s_cmp_lg_u64 s[0:1], 0
	s_nop 0
	v_addc_co_u32_e32 v31, vcc, 0, v63, vcc
	flat_load_dword v41, v[30:31]
	flat_load_dword v42, v[30:31] offset:2048
	v_add_co_u32_e32 v30, vcc, s2, v62
	s_mov_b32 s2, 0xc000
	s_nop 0
	v_addc_co_u32_e32 v31, vcc, 0, v63, vcc
	flat_load_dword v39, v[30:31]
	flat_load_dword v40, v[30:31] offset:2048
	v_add_co_u32_e32 v30, vcc, 0xb000, v62
	s_cselect_b64 s[24:25], -1, 0
	s_nop 0
	v_addc_co_u32_e32 v31, vcc, 0, v63, vcc
	flat_load_dword v37, v[30:31]
	flat_load_dword v38, v[30:31] offset:2048
	v_add_co_u32_e32 v30, vcc, s2, v62
	s_cmp_eq_u64 s[0:1], 0
	s_nop 0
	v_addc_co_u32_e32 v31, vcc, 0, v63, vcc
	flat_load_dword v35, v[30:31]
	flat_load_dword v36, v[30:31] offset:2048
	v_add_co_u32_e32 v30, vcc, 0xd000, v62
	v_add_lshl_u32 v28, s18, v2, 2
	s_nop 0
	v_addc_co_u32_e32 v31, vcc, 0, v63, vcc
	v_add_co_u32_e32 v64, vcc, 0xe000, v62
	flat_load_dword v33, v[30:31]
	flat_load_dword v34, v[30:31] offset:2048
	v_addc_co_u32_e32 v65, vcc, 0, v63, vcc
	v_add_co_u32_e32 v62, vcc, 0xf000, v62
	flat_load_dword v31, v[64:65]
	flat_load_dword v32, v[64:65] offset:2048
	v_addc_co_u32_e32 v63, vcc, 0, v63, vcc
	flat_load_dword v27, v[62:63]
	flat_load_dword v30, v[62:63] offset:2048
	s_cbranch_scc1 .LBB0_629
	v_lshlrev_b32_e32 v96, 2, v29
	v_lshl_add_u64 v[62:63], s[58:59], 0, v[96:97]
	global_load_dword v174, v[62:63], off
	global_load_dword v175, v[62:63], off offset:8
	global_load_dword v176, v[62:63], off offset:16
	global_load_dword v177, v[62:63], off offset:24
	global_load_dword v178, v[62:63], off offset:32
	global_load_dword v179, v[62:63], off offset:40
	global_load_dword v180, v[62:63], off offset:48
	global_load_dword v181, v[62:63], off offset:56
	global_load_dword v182, v[62:63], off offset:64
	global_load_dword v183, v[62:63], off offset:72
	global_load_dword v184, v[62:63], off offset:80
	global_load_dword v185, v[62:63], off offset:88
	global_load_dword v186, v[62:63], off offset:96
	global_load_dword v187, v[62:63], off offset:104
	global_load_dword v188, v[62:63], off offset:112
	global_load_dword v189, v[62:63], off offset:120
	global_load_dword v190, v[62:63], off offset:128
	global_load_dword v191, v[62:63], off offset:136
	global_load_dword v192, v[62:63], off offset:144
	global_load_dword v193, v[62:63], off offset:152
	global_load_dword v194, v[62:63], off offset:160
	global_load_dword v195, v[62:63], off offset:168
	global_load_dword v196, v[62:63], off offset:176
	global_load_dword v197, v[62:63], off offset:184
	global_load_dword v199, v[62:63], off offset:192
	global_load_dword v200, v[62:63], off offset:200
	global_load_dword v201, v[62:63], off offset:208
	global_load_dword v202, v[62:63], off offset:216
	global_load_dword v203, v[62:63], off offset:224
	global_load_dword v204, v[62:63], off offset:232
	global_load_dword v205, v[62:63], off offset:240
	global_load_dword v206, v[62:63], off offset:248
	s_nop 0
	s_mov_b64 s[0:1], 0
	s_waitcnt vmcnt(0) lgkmcnt(0)
	v_mul_f32_e32 v29, v59, v174
	ds_write_b32 v114, v29
	v_mov_b32_e32 v29, v97
	v_lshl_add_u64 v[62:63], s[58:59], 0, v[28:29]
	s_nop 0
	s_waitcnt vmcnt(0) lgkmcnt(0)
	v_mul_f32_e32 v29, v60, v175
	s_branch .LBB0_630

.LBB0_632:
	s_waitcnt vmcnt(0) lgkmcnt(0)
	v_add_u32_e32 v59, v1, v120
	ds_write_b32 v59, v29
	v_cndmask_b32_e64 v29, 0, 1, s[24:25]
	v_cmp_ne_u32_e64 s[0:1], 1, v29
	s_andn2_b64 vcc, exec, s[24:25]
	s_cbranch_vccnz .LBB0_634
	v_mov_b32_e32 v29, v97
	v_lshl_add_u64 v[60:61], s[58:59], 0, v[28:29]
	s_nop 0
	v_add_u32_e32 v59, v1, v121
	s_mov_b64 s[24:25], 0
	s_waitcnt vmcnt(0) lgkmcnt(0)
	v_mul_f32_e32 v29, v57, v176
	ds_write_b32 v59, v29
	s_nop 0
	s_waitcnt vmcnt(0) lgkmcnt(0)
	v_mul_f32_e32 v29, v58, v177
	s_branch .LBB0_635

.LBB0_637:
	v_add_u32_e32 v57, v1, v122
	s_and_b64 vcc, exec, s[0:1]
	ds_write_b32 v57, v29
	s_cbranch_vccnz .LBB0_639
	v_mov_b32_e32 v29, v97
	v_lshl_add_u64 v[58:59], s[58:59], 0, v[28:29]
	s_nop 0
	v_add_u32_e32 v57, v1, v123
	s_mov_b64 s[24:25], 0
	s_waitcnt vmcnt(0) lgkmcnt(0)
	v_mul_f32_e32 v29, v55, v178
	ds_write_b32 v57, v29
	s_nop 0
	s_waitcnt vmcnt(0) lgkmcnt(0)
	v_mul_f32_e32 v29, v56, v179
	s_branch .LBB0_640

.LBB0_642:
	v_add_u32_e32 v55, v1, v124
	s_and_b64 vcc, exec, s[0:1]
	ds_write_b32 v55, v29
	s_cbranch_vccnz .LBB0_644
	v_mov_b32_e32 v29, v97
	v_lshl_add_u64 v[56:57], s[58:59], 0, v[28:29]
	s_nop 0
	v_add_u32_e32 v55, v1, v125
	s_mov_b64 s[24:25], 0
	s_waitcnt vmcnt(0) lgkmcnt(0)
	v_mul_f32_e32 v29, v53, v180
	ds_write_b32 v55, v29
	s_nop 0
	s_waitcnt vmcnt(0) lgkmcnt(0)
	v_mul_f32_e32 v29, v54, v181
	s_branch .LBB0_645

.LBB0_647:
	v_add_u32_e32 v53, v1, v126
	s_and_b64 vcc, exec, s[0:1]
	ds_write_b32 v53, v29
	s_cbranch_vccnz .LBB0_649
	v_mov_b32_e32 v29, v97
	v_lshl_add_u64 v[54:55], s[58:59], 0, v[28:29]
	s_nop 0
	v_add_u32_e32 v53, v1, v127
	s_mov_b64 s[24:25], 0
	s_waitcnt vmcnt(0) lgkmcnt(0)
	v_mul_f32_e32 v29, v51, v182
	ds_write_b32 v53, v29
	s_nop 0
	s_waitcnt vmcnt(0) lgkmcnt(0)
	v_mul_f32_e32 v29, v52, v183
	s_branch .LBB0_650

.LBB0_652:
	v_add_u32_e32 v51, v1, v128
	s_and_b64 vcc, exec, s[0:1]
	ds_write_b32 v51, v29
	s_cbranch_vccnz .LBB0_654
	v_mov_b32_e32 v29, v97
	v_lshl_add_u64 v[52:53], s[58:59], 0, v[28:29]
	s_nop 0
	v_add_u32_e32 v51, v1, v129
	s_mov_b64 s[24:25], 0
	s_waitcnt vmcnt(0) lgkmcnt(0)
	v_mul_f32_e32 v29, v49, v184
	ds_write_b32 v51, v29
	s_nop 0
	s_waitcnt vmcnt(0) lgkmcnt(0)
	v_mul_f32_e32 v29, v50, v185
	s_branch .LBB0_655

.LBB0_657:
	v_add_u32_e32 v49, v1, v130
	s_and_b64 vcc, exec, s[0:1]
	ds_write_b32 v49, v29
	s_cbranch_vccnz .LBB0_659
	v_mov_b32_e32 v29, v97
	v_lshl_add_u64 v[50:51], s[58:59], 0, v[28:29]
	s_nop 0
	v_add_u32_e32 v49, v1, v131
	s_mov_b64 s[24:25], 0
	s_waitcnt vmcnt(0) lgkmcnt(0)
	v_mul_f32_e32 v29, v47, v186
	ds_write_b32 v49, v29
	s_nop 0
	s_waitcnt vmcnt(0) lgkmcnt(0)
	v_mul_f32_e32 v29, v48, v187
	s_branch .LBB0_660

.LBB0_662:
	v_add_u32_e32 v47, v1, v132
	s_and_b64 vcc, exec, s[0:1]
	ds_write_b32 v47, v29
	s_cbranch_vccnz .LBB0_664
	v_mov_b32_e32 v29, v97
	v_lshl_add_u64 v[48:49], s[58:59], 0, v[28:29]
	s_nop 0
	v_add_u32_e32 v47, v1, v133
	s_mov_b64 s[24:25], 0
	s_waitcnt vmcnt(0) lgkmcnt(0)
	v_mul_f32_e32 v29, v45, v188
	ds_write_b32 v47, v29
	s_nop 0
	s_waitcnt vmcnt(0) lgkmcnt(0)
	v_mul_f32_e32 v29, v46, v189
	s_branch .LBB0_665

.LBB0_667:
	v_add_u32_e32 v45, v1, v134
	s_and_b64 vcc, exec, s[0:1]
	ds_write_b32 v45, v29
	s_cbranch_vccnz .LBB0_669
	v_mov_b32_e32 v29, v97
	v_lshl_add_u64 v[46:47], s[58:59], 0, v[28:29]
	s_nop 0
	v_add_u32_e32 v45, v1, v135
	s_mov_b64 s[24:25], 0
	s_waitcnt vmcnt(0) lgkmcnt(0)
	v_mul_f32_e32 v29, v43, v190
	ds_write_b32 v45, v29
	s_nop 0
	s_waitcnt vmcnt(0) lgkmcnt(0)
	v_mul_f32_e32 v29, v44, v191
	s_branch .LBB0_670

.LBB0_672:
	v_add_u32_e32 v43, v1, v136
	s_and_b64 vcc, exec, s[0:1]
	ds_write_b32 v43, v29
	s_cbranch_vccnz .LBB0_674
	v_mov_b32_e32 v29, v97
	v_lshl_add_u64 v[44:45], s[58:59], 0, v[28:29]
	s_nop 0
	v_add_u32_e32 v43, v1, v137
	s_mov_b64 s[24:25], 0
	s_waitcnt vmcnt(0) lgkmcnt(0)
	v_mul_f32_e32 v29, v41, v192
	ds_write_b32 v43, v29
	s_nop 0
	s_waitcnt vmcnt(0) lgkmcnt(0)
	v_mul_f32_e32 v29, v42, v193
	s_branch .LBB0_675

.LBB0_677:
	v_add_u32_e32 v41, v1, v138
	s_and_b64 vcc, exec, s[0:1]
	ds_write_b32 v41, v29
	s_cbranch_vccnz .LBB0_679
	v_mov_b32_e32 v29, v97
	v_lshl_add_u64 v[42:43], s[58:59], 0, v[28:29]
	s_nop 0
	v_add_u32_e32 v41, v1, v139
	s_mov_b64 s[24:25], 0
	s_waitcnt vmcnt(0) lgkmcnt(0)
	v_mul_f32_e32 v29, v39, v194
	ds_write_b32 v41, v29
	s_nop 0
	s_waitcnt vmcnt(0) lgkmcnt(0)
	v_mul_f32_e32 v29, v40, v195
	s_branch .LBB0_680

.LBB0_682:
	v_add_u32_e32 v39, v1, v140
	s_and_b64 vcc, exec, s[0:1]
	ds_write_b32 v39, v29
	s_cbranch_vccnz .LBB0_684
	v_mov_b32_e32 v29, v97
	v_lshl_add_u64 v[40:41], s[58:59], 0, v[28:29]
	s_nop 0
	v_add_u32_e32 v39, v1, v141
	s_mov_b64 s[24:25], 0
	s_waitcnt vmcnt(0) lgkmcnt(0)
	v_mul_f32_e32 v29, v37, v196
	ds_write_b32 v39, v29
	s_nop 0
	s_waitcnt vmcnt(0) lgkmcnt(0)
	v_mul_f32_e32 v29, v38, v197
	s_branch .LBB0_685

.LBB0_687:
	v_add_u32_e32 v37, v1, v142
	s_and_b64 vcc, exec, s[0:1]
	ds_write_b32 v37, v29
	s_cbranch_vccnz .LBB0_689
	v_mov_b32_e32 v29, v97
	v_lshl_add_u64 v[38:39], s[58:59], 0, v[28:29]
	s_nop 0
	v_add_u32_e32 v37, v1, v143
	s_mov_b64 s[24:25], 0
	s_waitcnt vmcnt(0) lgkmcnt(0)
	v_mul_f32_e32 v29, v35, v199
	ds_write_b32 v37, v29
	s_nop 0
	s_waitcnt vmcnt(0) lgkmcnt(0)
	v_mul_f32_e32 v29, v36, v200
	s_branch .LBB0_690

.LBB0_692:
	v_add_u32_e32 v35, v1, v144
	s_and_b64 vcc, exec, s[0:1]
	ds_write_b32 v35, v29
	s_cbranch_vccnz .LBB0_694
	v_mov_b32_e32 v29, v97
	v_lshl_add_u64 v[36:37], s[58:59], 0, v[28:29]
	s_nop 0
	s_mov_b64 s[24:25], 0
	s_waitcnt vmcnt(0) lgkmcnt(0)
	v_mul_f32_e32 v29, v33, v201
	ds_write_b32 v35, v29 offset:264
	s_nop 0
	s_waitcnt vmcnt(0) lgkmcnt(0)
	v_mul_f32_e32 v29, v34, v202
	s_branch .LBB0_695

.LBB0_697:
	s_and_b64 vcc, exec, s[0:1]
	ds_write_b32 v35, v29 offset:528
	s_cbranch_vccnz .LBB0_699
	v_mov_b32_e32 v29, v97
	v_lshl_add_u64 v[36:37], s[58:59], 0, v[28:29]
	s_nop 0
	s_mov_b64 s[24:25], 0
	s_waitcnt vmcnt(0) lgkmcnt(0)
	v_mul_f32_e32 v29, v31, v203
	ds_write_b32 v35, v29 offset:792
	s_nop 0
	s_waitcnt vmcnt(0) lgkmcnt(0)
	v_mul_f32_e32 v29, v32, v204
	s_branch .LBB0_700

.LBB0_702:
	s_and_b64 vcc, exec, s[0:1]
	ds_write_b32 v35, v29 offset:1056
	s_cbranch_vccnz .LBB0_704
	v_mov_b32_e32 v29, v97
	v_lshl_add_u64 v[28:29], s[58:59], 0, v[28:29]
	s_nop 0
	s_mov_b64 s[0:1], 0
	s_waitcnt vmcnt(0) lgkmcnt(0)
	v_mul_f32_e32 v31, v27, v205
	ds_write_b32 v35, v31 offset:1320
	s_nop 0
	s_waitcnt vmcnt(0) lgkmcnt(0)
	v_mul_f32_e32 v28, v30, v206
	s_branch .LBB0_705

.LBB0_734:
	s_add_u32 s2, s2, s43
	s_addc_u32 s8, s8, s42
	s_lshl_b64 s[20:21], s[60:61], 2
	s_add_u32 s58, s0, s20
	s_addc_u32 s59, s1, s21
	s_ashr_i32 s25, s24, 31
	s_lshl_b32 s16, s14, 6
	s_lshl_b64 s[14:15], s[24:25], 2
	s_add_u32 s14, s2, s14
	v_or_b32_e32 v61, s16, v2
	s_addc_u32 s15, s8, s15
	v_lshlrev_b32_e32 v96, 2, v0
	v_lshl_add_u64 v[28:29], s[14:15], 0, v[96:97]
	s_movk_i32 s2, 0x5400
	v_mul_u32_u24_e32 v96, 0x1500, v61
	v_mad_u64_u32 v[30:31], s[14:15], v61, s2, v[28:29]
	v_lshl_add_u64 v[28:29], v[96:97], 2, v[28:29]
	s_mov_b32 s2, 0xa000
	flat_load_dword v59, v[30:31]
	v_add_co_u32_e32 v30, vcc, s2, v28
	s_mov_b32 s2, 0x15000
	s_nop 0
	v_addc_co_u32_e32 v31, vcc, 0, v29, vcc
	flat_load_dword v60, v[30:31] offset:2048
	v_add_co_u32_e32 v30, vcc, s2, v28
	s_mov_b32 s2, 0x1f000
	s_nop 0
	v_addc_co_u32_e32 v31, vcc, 0, v29, vcc
	flat_load_dword v57, v[30:31]
	v_add_co_u32_e32 v30, vcc, s2, v28
	s_mov_b32 s2, 0x2a000
	s_nop 0
	v_addc_co_u32_e32 v31, vcc, 0, v29, vcc
	flat_load_dword v58, v[30:31] offset:2048
	v_add_co_u32_e32 v30, vcc, s2, v28
	s_mov_b32 s2, 0x34000
	s_nop 0
	v_addc_co_u32_e32 v31, vcc, 0, v29, vcc
	flat_load_dword v54, v[30:31]
	v_add_co_u32_e32 v30, vcc, s2, v28
	s_mov_b32 s2, 0x3f000
	s_nop 0
	v_addc_co_u32_e32 v31, vcc, 0, v29, vcc
	flat_load_dword v56, v[30:31] offset:2048
	v_add_co_u32_e32 v30, vcc, s2, v28
	s_mov_b32 s2, 0x49000
	s_nop 0
	v_addc_co_u32_e32 v31, vcc, 0, v29, vcc
	flat_load_dword v53, v[30:31]
	v_add_co_u32_e32 v30, vcc, s2, v28
	s_mov_b32 s2, 0x54000
	s_nop 0
	v_addc_co_u32_e32 v31, vcc, 0, v29, vcc
	flat_load_dword v55, v[30:31] offset:2048
	v_add_co_u32_e32 v30, vcc, s2, v28
	s_mov_b32 s2, 0x5e000
	s_nop 0
	v_addc_co_u32_e32 v31, vcc, 0, v29, vcc
	flat_load_dword v51, v[30:31]
	v_add_co_u32_e32 v30, vcc, s2, v28
	s_mov_b32 s2, 0x69000
	s_nop 0
	v_addc_co_u32_e32 v31, vcc, 0, v29, vcc
	flat_load_dword v52, v[30:31] offset:2048
	v_add_co_u32_e32 v30, vcc, s2, v28
	s_mov_b32 s2, 0x73000
	s_nop 0
	v_addc_co_u32_e32 v31, vcc, 0, v29, vcc
	flat_load_dword v49, v[30:31]
	v_add_co_u32_e32 v30, vcc, s2, v28
	s_mov_b32 s2, 0x7e000
	s_nop 0
	v_addc_co_u32_e32 v31, vcc, 0, v29, vcc
	flat_load_dword v50, v[30:31] offset:2048
	v_add_co_u32_e32 v30, vcc, s2, v28
	s_mov_b32 s2, 0x88000
	s_nop 0
	v_addc_co_u32_e32 v31, vcc, 0, v29, vcc
	flat_load_dword v46, v[30:31]
	v_add_co_u32_e32 v30, vcc, s2, v28
	s_mov_b32 s2, 0x93000
	s_nop 0
	v_addc_co_u32_e32 v31, vcc, 0, v29, vcc
	flat_load_dword v48, v[30:31] offset:2048
	v_add_co_u32_e32 v30, vcc, s2, v28
	s_mov_b32 s2, 0x9d000
	s_nop 0
	v_addc_co_u32_e32 v31, vcc, 0, v29, vcc
	flat_load_dword v45, v[30:31]
	v_add_co_u32_e32 v30, vcc, s2, v28
	s_mov_b32 s2, 0xa8000
	s_nop 0
	v_addc_co_u32_e32 v31, vcc, 0, v29, vcc
	flat_load_dword v47, v[30:31] offset:2048
	v_add_co_u32_e32 v30, vcc, s2, v28
	s_mov_b32 s2, 0xb2000
	s_nop 0
	v_addc_co_u32_e32 v31, vcc, 0, v29, vcc
	flat_load_dword v43, v[30:31]
	v_add_co_u32_e32 v30, vcc, s2, v28
	s_mov_b32 s2, 0xbd000
	s_nop 0
	v_addc_co_u32_e32 v31, vcc, 0, v29, vcc
	flat_load_dword v44, v[30:31] offset:2048
	v_add_co_u32_e32 v30, vcc, s2, v28
	s_mov_b32 s2, 0xc7000
	s_nop 0
	v_addc_co_u32_e32 v31, vcc, 0, v29, vcc
	flat_load_dword v41, v[30:31]
	v_add_co_u32_e32 v30, vcc, s2, v28
	s_mov_b32 s2, 0xd2000
	s_nop 0
	v_addc_co_u32_e32 v31, vcc, 0, v29, vcc
	flat_load_dword v42, v[30:31] offset:2048
	v_add_co_u32_e32 v30, vcc, s2, v28
	s_mov_b32 s2, 0xdc000
	s_nop 0
	v_addc_co_u32_e32 v31, vcc, 0, v29, vcc
	flat_load_dword v38, v[30:31]
	v_add_co_u32_e32 v30, vcc, s2, v28
	s_mov_b32 s2, 0xe7000
	s_nop 0
	v_addc_co_u32_e32 v31, vcc, 0, v29, vcc
	flat_load_dword v40, v[30:31] offset:2048
	v_add_co_u32_e32 v30, vcc, s2, v28
	s_mov_b32 s2, 0xf1000
	s_nop 0
	v_addc_co_u32_e32 v31, vcc, 0, v29, vcc
	flat_load_dword v37, v[30:31]
	v_add_co_u32_e32 v30, vcc, s2, v28
	s_mov_b32 s2, 0xfc000
	s_nop 0
	v_addc_co_u32_e32 v31, vcc, 0, v29, vcc
	flat_load_dword v39, v[30:31] offset:2048
	v_add_co_u32_e32 v30, vcc, s2, v28
	s_mov_b32 s2, 0x106000
	s_nop 0
	v_addc_co_u32_e32 v31, vcc, 0, v29, vcc
	flat_load_dword v35, v[30:31]
	v_add_co_u32_e32 v30, vcc, s2, v28
	s_mov_b32 s2, 0x111000
	s_nop 0
	v_addc_co_u32_e32 v31, vcc, 0, v29, vcc
	flat_load_dword v36, v[30:31] offset:2048
	v_add_co_u32_e32 v30, vcc, s2, v28
	s_mov_b32 s2, 0x11b000
	s_nop 0
	v_addc_co_u32_e32 v31, vcc, 0, v29, vcc
	flat_load_dword v33, v[30:31]
	v_add_co_u32_e32 v30, vcc, s2, v28
	s_mov_b32 s2, 0x126000
	s_nop 0
	v_addc_co_u32_e32 v31, vcc, 0, v29, vcc
	flat_load_dword v34, v[30:31] offset:2048
	v_add_co_u32_e32 v30, vcc, s2, v28
	s_cmp_lg_u64 s[0:1], 0
	s_nop 0
	v_addc_co_u32_e32 v31, vcc, 0, v29, vcc
	v_add_co_u32_e32 v62, vcc, 0x130000, v28
	flat_load_dword v30, v[30:31]
	s_nop 0
	v_addc_co_u32_e32 v63, vcc, 0, v29, vcc
	flat_load_dword v31, v[62:63] offset:2048
	v_add_co_u32_e32 v62, vcc, 0x13b000, v28
	s_cselect_b64 s[24:25], -1, 0
	s_nop 0
	v_addc_co_u32_e32 v63, vcc, 0, v29, vcc
	v_add_co_u32_e32 v28, vcc, 0x145000, v28
	flat_load_dword v27, v[62:63]
	s_nop 0
	v_addc_co_u32_e32 v29, vcc, 0, v29, vcc
	flat_load_dword v32, v[28:29] offset:2048
	s_cmp_eq_u64 s[0:1], 0
	v_add_lshl_u32 v28, s16, v2, 2
	s_cbranch_scc1 .LBB0_916
	v_lshlrev_b32_e32 v96, 2, v61
	v_lshl_add_u64 v[62:63], s[58:59], 0, v[96:97]
	global_load_dword v174, v[62:63], off
	global_load_dword v175, v[62:63], off offset:8
	global_load_dword v176, v[62:63], off offset:16
	global_load_dword v177, v[62:63], off offset:24
	global_load_dword v178, v[62:63], off offset:32
	global_load_dword v179, v[62:63], off offset:40
	global_load_dword v180, v[62:63], off offset:48
	global_load_dword v181, v[62:63], off offset:56
	global_load_dword v182, v[62:63], off offset:64
	global_load_dword v183, v[62:63], off offset:72
	global_load_dword v184, v[62:63], off offset:80
	global_load_dword v185, v[62:63], off offset:88
	global_load_dword v186, v[62:63], off offset:96
	global_load_dword v187, v[62:63], off offset:104
	global_load_dword v188, v[62:63], off offset:112
	global_load_dword v189, v[62:63], off offset:120
	global_load_dword v190, v[62:63], off offset:128
	global_load_dword v191, v[62:63], off offset:136
	global_load_dword v192, v[62:63], off offset:144
	global_load_dword v193, v[62:63], off offset:152
	global_load_dword v194, v[62:63], off offset:160
	global_load_dword v195, v[62:63], off offset:168
	global_load_dword v196, v[62:63], off offset:176
	global_load_dword v197, v[62:63], off offset:184
	global_load_dword v199, v[62:63], off offset:192
	global_load_dword v200, v[62:63], off offset:200
	global_load_dword v201, v[62:63], off offset:208
	global_load_dword v202, v[62:63], off offset:216
	global_load_dword v203, v[62:63], off offset:224
	global_load_dword v204, v[62:63], off offset:232
	global_load_dword v205, v[62:63], off offset:240
	global_load_dword v206, v[62:63], off offset:248
	s_nop 0
	s_waitcnt vmcnt(0) lgkmcnt(0)
	v_mul_f32_e32 v29, v59, v174
	ds_write_b32 v114, v29
	v_mov_b32_e32 v29, v97
	v_lshl_add_u64 v[62:63], s[58:59], 0, v[28:29]
	s_nop 0
	s_waitcnt vmcnt(0) lgkmcnt(0)
	v_mul_f32_e32 v29, v60, v175
	s_cbranch_execnz .LBB0_737

.LBB0_737:
	s_waitcnt vmcnt(0) lgkmcnt(0)
	v_add_u32_e32 v59, v1, v120
	ds_write_b32 v59, v29
	v_cndmask_b32_e64 v29, 0, 1, s[24:25]
	v_cmp_ne_u32_e64 s[0:1], 1, v29
	s_andn2_b64 vcc, exec, s[24:25]
	s_cbranch_vccnz .LBB0_917
	v_mov_b32_e32 v29, v97
	v_lshl_add_u64 v[60:61], s[58:59], 0, v[28:29]
	s_nop 0
	v_add_u32_e32 v59, v1, v121
	s_waitcnt vmcnt(0) lgkmcnt(0)
	v_mul_f32_e32 v29, v57, v176
	ds_write_b32 v59, v29
	s_nop 0
	s_waitcnt vmcnt(0) lgkmcnt(0)
	v_mul_f32_e32 v29, v58, v177
	s_cbranch_execnz .LBB0_740

.LBB0_740:
	v_add_u32_e32 v57, v1, v122
	s_and_b64 vcc, exec, s[0:1]
	ds_write_b32 v57, v29
	s_cbranch_vccnz .LBB0_918
	v_mov_b32_e32 v29, v97
	v_lshl_add_u64 v[58:59], s[58:59], 0, v[28:29]
	s_nop 0
	v_add_u32_e32 v57, v1, v123
	s_waitcnt vmcnt(0) lgkmcnt(0)
	v_mul_f32_e32 v29, v54, v178
	ds_write_b32 v57, v29
	s_nop 0
	s_waitcnt vmcnt(0) lgkmcnt(0)
	v_mul_f32_e32 v29, v56, v179
	s_cbranch_execnz .LBB0_743

.LBB0_743:
	v_add_u32_e32 v54, v1, v124
	s_and_b64 vcc, exec, s[0:1]
	ds_write_b32 v54, v29
	s_cbranch_vccnz .LBB0_919
	v_mov_b32_e32 v29, v97
	v_lshl_add_u64 v[56:57], s[58:59], 0, v[28:29]
	s_nop 0
	v_add_u32_e32 v54, v1, v125
	s_waitcnt vmcnt(0) lgkmcnt(0)
	v_mul_f32_e32 v29, v53, v180
	ds_write_b32 v54, v29
	s_nop 0
	s_waitcnt vmcnt(0) lgkmcnt(0)
	v_mul_f32_e32 v29, v55, v181
	s_cbranch_execnz .LBB0_746

.LBB0_746:
	v_add_u32_e32 v53, v1, v126
	s_and_b64 vcc, exec, s[0:1]
	ds_write_b32 v53, v29
	s_cbranch_vccnz .LBB0_920
	v_mov_b32_e32 v29, v97
	v_lshl_add_u64 v[54:55], s[58:59], 0, v[28:29]
	s_nop 0
	v_add_u32_e32 v53, v1, v127
	s_waitcnt vmcnt(0) lgkmcnt(0)
	v_mul_f32_e32 v29, v51, v182
	ds_write_b32 v53, v29
	s_nop 0
	s_waitcnt vmcnt(0) lgkmcnt(0)
	v_mul_f32_e32 v29, v52, v183
	s_cbranch_execnz .LBB0_749

.LBB0_749:
	v_add_u32_e32 v51, v1, v128
	s_and_b64 vcc, exec, s[0:1]
	ds_write_b32 v51, v29
	s_cbranch_vccnz .LBB0_921
	v_mov_b32_e32 v29, v97
	v_lshl_add_u64 v[52:53], s[58:59], 0, v[28:29]
	s_nop 0
	v_add_u32_e32 v51, v1, v129
	s_waitcnt vmcnt(0) lgkmcnt(0)
	v_mul_f32_e32 v29, v49, v184
	ds_write_b32 v51, v29
	s_nop 0
	s_waitcnt vmcnt(0) lgkmcnt(0)
	v_mul_f32_e32 v29, v50, v185
	s_cbranch_execnz .LBB0_752

.LBB0_752:
	v_add_u32_e32 v49, v1, v130
	s_and_b64 vcc, exec, s[0:1]
	ds_write_b32 v49, v29
	s_cbranch_vccnz .LBB0_922
	v_mov_b32_e32 v29, v97
	v_lshl_add_u64 v[50:51], s[58:59], 0, v[28:29]
	s_nop 0
	v_add_u32_e32 v49, v1, v131
	s_waitcnt vmcnt(0) lgkmcnt(0)
	v_mul_f32_e32 v29, v46, v186
	ds_write_b32 v49, v29
	s_nop 0
	s_waitcnt vmcnt(0) lgkmcnt(0)
	v_mul_f32_e32 v29, v48, v187
	s_cbranch_execnz .LBB0_755

.LBB0_755:
	v_add_u32_e32 v46, v1, v132
	s_and_b64 vcc, exec, s[0:1]
	ds_write_b32 v46, v29
	s_cbranch_vccnz .LBB0_923
	v_mov_b32_e32 v29, v97
	v_lshl_add_u64 v[48:49], s[58:59], 0, v[28:29]
	s_nop 0
	v_add_u32_e32 v46, v1, v133
	s_waitcnt vmcnt(0) lgkmcnt(0)
	v_mul_f32_e32 v29, v45, v188
	ds_write_b32 v46, v29
	s_nop 0
	s_waitcnt vmcnt(0) lgkmcnt(0)
	v_mul_f32_e32 v29, v47, v189
	s_cbranch_execnz .LBB0_758

.LBB0_758:
	v_add_u32_e32 v45, v1, v134
	s_and_b64 vcc, exec, s[0:1]
	ds_write_b32 v45, v29
	s_cbranch_vccnz .LBB0_924
	v_mov_b32_e32 v29, v97
	v_lshl_add_u64 v[46:47], s[58:59], 0, v[28:29]
	s_nop 0
	v_add_u32_e32 v45, v1, v135
	s_waitcnt vmcnt(0) lgkmcnt(0)
	v_mul_f32_e32 v29, v43, v190
	ds_write_b32 v45, v29
	s_nop 0
	s_waitcnt vmcnt(0) lgkmcnt(0)
	v_mul_f32_e32 v29, v44, v191
	s_cbranch_execnz .LBB0_761

.LBB0_761:
	v_add_u32_e32 v43, v1, v136
	s_and_b64 vcc, exec, s[0:1]
	ds_write_b32 v43, v29
	s_cbranch_vccnz .LBB0_925
	v_mov_b32_e32 v29, v97
	v_lshl_add_u64 v[44:45], s[58:59], 0, v[28:29]
	s_nop 0
	v_add_u32_e32 v43, v1, v137
	s_waitcnt vmcnt(0) lgkmcnt(0)
	v_mul_f32_e32 v29, v41, v192
	ds_write_b32 v43, v29
	s_nop 0
	s_waitcnt vmcnt(0) lgkmcnt(0)
	v_mul_f32_e32 v29, v42, v193
	s_cbranch_execnz .LBB0_764

.LBB0_764:
	v_add_u32_e32 v41, v1, v138
	s_and_b64 vcc, exec, s[0:1]
	ds_write_b32 v41, v29
	s_cbranch_vccnz .LBB0_926
	v_mov_b32_e32 v29, v97
	v_lshl_add_u64 v[42:43], s[58:59], 0, v[28:29]
	s_nop 0
	v_add_u32_e32 v41, v1, v139
	s_waitcnt vmcnt(0) lgkmcnt(0)
	v_mul_f32_e32 v29, v38, v194
	ds_write_b32 v41, v29
	s_nop 0
	s_waitcnt vmcnt(0) lgkmcnt(0)
	v_mul_f32_e32 v29, v40, v195
	s_cbranch_execnz .LBB0_767

.LBB0_767:
	v_add_u32_e32 v38, v1, v140
	s_and_b64 vcc, exec, s[0:1]
	ds_write_b32 v38, v29
	s_cbranch_vccnz .LBB0_927
	v_mov_b32_e32 v29, v97
	v_lshl_add_u64 v[40:41], s[58:59], 0, v[28:29]
	s_nop 0
	v_add_u32_e32 v38, v1, v141
	s_waitcnt vmcnt(0) lgkmcnt(0)
	v_mul_f32_e32 v29, v37, v196
	ds_write_b32 v38, v29
	s_nop 0
	s_waitcnt vmcnt(0) lgkmcnt(0)
	v_mul_f32_e32 v29, v39, v197
	s_cbranch_execnz .LBB0_770

.LBB0_770:
	v_add_u32_e32 v37, v1, v142
	s_and_b64 vcc, exec, s[0:1]
	ds_write_b32 v37, v29
	s_cbranch_vccnz .LBB0_928
	v_mov_b32_e32 v29, v97
	v_lshl_add_u64 v[38:39], s[58:59], 0, v[28:29]
	s_nop 0
	v_add_u32_e32 v37, v1, v143
	s_waitcnt vmcnt(0) lgkmcnt(0)
	v_mul_f32_e32 v29, v35, v199
	ds_write_b32 v37, v29
	s_nop 0
	s_waitcnt vmcnt(0) lgkmcnt(0)
	v_mul_f32_e32 v29, v36, v200
	s_cbranch_execnz .LBB0_773

.LBB0_773:
	v_add_u32_e32 v35, v1, v144
	s_and_b64 vcc, exec, s[0:1]
	ds_write_b32 v35, v29
	s_cbranch_vccnz .LBB0_929
	v_mov_b32_e32 v29, v97
	v_lshl_add_u64 v[36:37], s[58:59], 0, v[28:29]
	s_nop 0
	s_waitcnt vmcnt(0) lgkmcnt(0)
	v_mul_f32_e32 v29, v33, v201
	ds_write_b32 v35, v29 offset:264
	s_nop 0
	s_waitcnt vmcnt(0) lgkmcnt(0)
	v_mul_f32_e32 v29, v34, v202
	s_cbranch_execnz .LBB0_776

.LBB0_776:
	s_and_b64 vcc, exec, s[0:1]
	ds_write_b32 v35, v29 offset:528
	s_cbranch_vccnz .LBB0_930
	v_mov_b32_e32 v29, v97
	v_lshl_add_u64 v[36:37], s[58:59], 0, v[28:29]
	s_nop 0
	s_waitcnt vmcnt(0) lgkmcnt(0)
	v_mul_f32_e32 v29, v30, v203
	ds_write_b32 v35, v29 offset:792
	s_nop 0
	s_waitcnt vmcnt(0) lgkmcnt(0)
	v_mul_f32_e32 v29, v31, v204
	s_cbranch_execnz .LBB0_779

.LBB0_779:
	s_and_b64 vcc, exec, s[0:1]
	ds_write_b32 v35, v29 offset:1056
	s_cbranch_vccnz .LBB0_931
	v_mov_b32_e32 v29, v97
	v_lshl_add_u64 v[28:29], s[58:59], 0, v[28:29]
	s_nop 0
	s_waitcnt vmcnt(0) lgkmcnt(0)
	v_mul_f32_e32 v30, v27, v205
	ds_write_b32 v35, v30 offset:1320
	s_nop 0
	s_waitcnt vmcnt(0) lgkmcnt(0)
	v_mul_f32_e32 v28, v32, v206
	s_cbranch_execnz .LBB0_782

.LBB0_784:
	s_andn2_b64 vcc, exec, s[0:1]
	s_cbranch_vccnz .LBB0_834
	v_mov_b32_e32 v27, 0x204f0
	s_add_i32 s2, s78, 0xfffff500
	v_add_u32_e32 v27, 0, v27
	ds_read2_b32 v[28:29], v27 offset1:1
	v_mov_b32_e32 v27, 0x204e8
	v_lshlrev_b32_e32 v96, 2, v0
	v_add_u32_e32 v27, 0, v27
	s_waitcnt lgkmcnt(0)
	v_readfirstlane_b32 s0, v28
	v_readfirstlane_b32 s1, v29
	ds_read2_b32 v[28:29], v27 offset1:1
	s_add_u32 s8, s0, s47
	s_addc_u32 s19, s1, s45
	s_lshl_b64 s[14:15], s[60:61], 2
	s_waitcnt lgkmcnt(0)
	v_readfirstlane_b32 s0, v28
	v_readfirstlane_b32 s1, v29
	s_add_u32 s58, s0, s14
	s_mul_i32 s14, s2, 0xba2f
	s_addc_u32 s59, s1, s15
	s_lshr_b32 s15, s14, 23
	s_mul_i32 s14, s15, 0xffffff50
	s_add_i32 s14, s14, s2
	s_lshl_b32 s18, s14, 5
	s_lshl_b32 s14, s14, 4
	s_and_b32 s2, s18, 0xe0
	s_and_b32 s14, s14, 0xffffff80
	s_or_b32 s16, s14, s2
	s_add_i32 s14, s2, s14
	s_addk_i32 s14, 0xa80
	s_cmpk_lt_u32 s2, 0x80
	s_cselect_b32 s14, s16, s14
	s_lshl_b32 s16, s15, 6
	s_ashr_i32 s15, s14, 31
	s_lshl_b64 s[14:15], s[14:15], 2
	s_add_u32 s14, s8, s14
	v_or_b32_e32 v61, s16, v2
	s_addc_u32 s15, s19, s15
	v_lshl_add_u64 v[28:29], s[14:15], 0, v[96:97]
	v_mul_u32_u24_e32 v96, 0x5800, v61
	v_mad_u64_u32 v[30:31], s[14:15], v61, s3, v[28:29]
	v_lshl_add_u64 v[28:29], v[28:29], 0, v[96:97]
	s_mov_b32 s2, 0xb000
	flat_load_dword v59, v[30:31]
	v_add_co_u32_e32 v30, vcc, s2, v28
	s_mov_b32 s2, 0x16000
	s_nop 0
	v_addc_co_u32_e32 v31, vcc, 0, v29, vcc
	flat_load_dword v60, v[30:31]
	v_add_co_u32_e32 v30, vcc, s2, v28
	s_mov_b32 s2, 0x21000
	s_nop 0
	v_addc_co_u32_e32 v31, vcc, 0, v29, vcc
	flat_load_dword v57, v[30:31]
	v_add_co_u32_e32 v30, vcc, s2, v28
	s_mov_b32 s2, 0x2c000
	s_nop 0
	v_addc_co_u32_e32 v31, vcc, 0, v29, vcc
	flat_load_dword v58, v[30:31]
	v_add_co_u32_e32 v30, vcc, s2, v28
	s_mov_b32 s2, 0x37000
	s_nop 0
	v_addc_co_u32_e32 v31, vcc, 0, v29, vcc
	flat_load_dword v54, v[30:31]
	v_add_co_u32_e32 v30, vcc, s2, v28
	s_mov_b32 s2, 0x42000
	s_nop 0
	v_addc_co_u32_e32 v31, vcc, 0, v29, vcc
	flat_load_dword v56, v[30:31]
	v_add_co_u32_e32 v30, vcc, s2, v28
	s_mov_b32 s2, 0x4d000
	s_nop 0
	v_addc_co_u32_e32 v31, vcc, 0, v29, vcc
	flat_load_dword v53, v[30:31]
	v_add_co_u32_e32 v30, vcc, s2, v28
	s_mov_b32 s2, 0x58000
	s_nop 0
	v_addc_co_u32_e32 v31, vcc, 0, v29, vcc
	flat_load_dword v55, v[30:31]
	v_add_co_u32_e32 v30, vcc, s2, v28
	s_mov_b32 s2, 0x63000
	s_nop 0
	v_addc_co_u32_e32 v31, vcc, 0, v29, vcc
	flat_load_dword v51, v[30:31]
	v_add_co_u32_e32 v30, vcc, s2, v28
	s_mov_b32 s2, 0x6e000
	s_nop 0
	v_addc_co_u32_e32 v31, vcc, 0, v29, vcc
	flat_load_dword v52, v[30:31]
	v_add_co_u32_e32 v30, vcc, s2, v28
	s_mov_b32 s2, 0x79000
	s_nop 0
	v_addc_co_u32_e32 v31, vcc, 0, v29, vcc
	flat_load_dword v49, v[30:31]
	v_add_co_u32_e32 v30, vcc, s2, v28
	s_mov_b32 s2, 0x84000
	s_nop 0
	v_addc_co_u32_e32 v31, vcc, 0, v29, vcc
	flat_load_dword v50, v[30:31]
	v_add_co_u32_e32 v30, vcc, s2, v28
	s_mov_b32 s2, 0x8f000
	s_nop 0
	v_addc_co_u32_e32 v31, vcc, 0, v29, vcc
	flat_load_dword v46, v[30:31]
	v_add_co_u32_e32 v30, vcc, s2, v28
	s_mov_b32 s2, 0x9a000
	s_nop 0
	v_addc_co_u32_e32 v31, vcc, 0, v29, vcc
	flat_load_dword v48, v[30:31]
	v_add_co_u32_e32 v30, vcc, s2, v28
	s_mov_b32 s2, 0xa5000
	s_nop 0
	v_addc_co_u32_e32 v31, vcc, 0, v29, vcc
	flat_load_dword v45, v[30:31]
	v_add_co_u32_e32 v30, vcc, s2, v28
	s_mov_b32 s2, 0xb0000
	s_nop 0
	v_addc_co_u32_e32 v31, vcc, 0, v29, vcc
	flat_load_dword v47, v[30:31]
	v_add_co_u32_e32 v30, vcc, s2, v28
	s_mov_b32 s2, 0xbb000
	s_nop 0
	v_addc_co_u32_e32 v31, vcc, 0, v29, vcc
	flat_load_dword v43, v[30:31]
	v_add_co_u32_e32 v30, vcc, s2, v28
	s_mov_b32 s2, 0xc6000
	s_nop 0
	v_addc_co_u32_e32 v31, vcc, 0, v29, vcc
	flat_load_dword v44, v[30:31]
	v_add_co_u32_e32 v30, vcc, s2, v28
	s_mov_b32 s2, 0xd1000
	s_nop 0
	v_addc_co_u32_e32 v31, vcc, 0, v29, vcc
	flat_load_dword v41, v[30:31]
	v_add_co_u32_e32 v30, vcc, s2, v28
	s_mov_b32 s2, 0xdc000
	s_nop 0
	v_addc_co_u32_e32 v31, vcc, 0, v29, vcc
	flat_load_dword v42, v[30:31]
	v_add_co_u32_e32 v30, vcc, s2, v28
	s_mov_b32 s2, 0xe7000
	s_nop 0
	v_addc_co_u32_e32 v31, vcc, 0, v29, vcc
	flat_load_dword v38, v[30:31]
	v_add_co_u32_e32 v30, vcc, s2, v28
	s_mov_b32 s2, 0xf2000
	s_nop 0
	v_addc_co_u32_e32 v31, vcc, 0, v29, vcc
	flat_load_dword v40, v[30:31]
	v_add_co_u32_e32 v30, vcc, s2, v28
	s_mov_b32 s2, 0xfd000
	s_nop 0
	v_addc_co_u32_e32 v31, vcc, 0, v29, vcc
	flat_load_dword v37, v[30:31]
	v_add_co_u32_e32 v30, vcc, s2, v28
	s_mov_b32 s2, 0x108000
	s_nop 0
	v_addc_co_u32_e32 v31, vcc, 0, v29, vcc
	flat_load_dword v39, v[30:31]
	v_add_co_u32_e32 v30, vcc, s2, v28
	s_mov_b32 s2, 0x113000
	s_nop 0
	v_addc_co_u32_e32 v31, vcc, 0, v29, vcc
	flat_load_dword v35, v[30:31]
	v_add_co_u32_e32 v30, vcc, s2, v28
	s_mov_b32 s2, 0x11e000
	s_nop 0
	v_addc_co_u32_e32 v31, vcc, 0, v29, vcc
	flat_load_dword v36, v[30:31]
	v_add_co_u32_e32 v30, vcc, s2, v28
	s_mov_b32 s2, 0x129000
	s_nop 0
	v_addc_co_u32_e32 v31, vcc, 0, v29, vcc
	flat_load_dword v33, v[30:31]
	v_add_co_u32_e32 v30, vcc, s2, v28
	s_mov_b32 s2, 0x134000
	s_nop 0
	v_addc_co_u32_e32 v31, vcc, 0, v29, vcc
	flat_load_dword v34, v[30:31]
	v_add_co_u32_e32 v30, vcc, s2, v28
	s_cmp_lg_u64 s[0:1], 0
	s_nop 0
	v_addc_co_u32_e32 v31, vcc, 0, v29, vcc
	v_add_co_u32_e32 v62, vcc, 0x13f000, v28
	flat_load_dword v30, v[30:31]
	s_nop 0
	v_addc_co_u32_e32 v63, vcc, 0, v29, vcc
	flat_load_dword v31, v[62:63]
	v_add_co_u32_e32 v62, vcc, 0x14a000, v28
	s_cselect_b64 s[24:25], -1, 0
	s_nop 0
	v_addc_co_u32_e32 v63, vcc, 0, v29, vcc
	v_add_co_u32_e32 v28, vcc, 0x155000, v28
	flat_load_dword v27, v[62:63]
	s_nop 0
	v_addc_co_u32_e32 v29, vcc, 0, v29, vcc
	flat_load_dword v32, v[28:29]
	s_cmp_eq_u64 s[0:1], 0
	v_add_lshl_u32 v28, s16, v2, 2
	s_cbranch_scc1 .LBB0_900
	v_lshlrev_b32_e32 v96, 2, v61
	v_lshl_add_u64 v[62:63], s[58:59], 0, v[96:97]
	global_load_dword v174, v[62:63], off
	global_load_dword v175, v[62:63], off offset:8
	global_load_dword v176, v[62:63], off offset:16
	global_load_dword v177, v[62:63], off offset:24
	global_load_dword v178, v[62:63], off offset:32
	global_load_dword v179, v[62:63], off offset:40
	global_load_dword v180, v[62:63], off offset:48
	global_load_dword v181, v[62:63], off offset:56
	global_load_dword v182, v[62:63], off offset:64
	global_load_dword v183, v[62:63], off offset:72
	global_load_dword v184, v[62:63], off offset:80
	global_load_dword v185, v[62:63], off offset:88
	global_load_dword v186, v[62:63], off offset:96
	global_load_dword v187, v[62:63], off offset:104
	global_load_dword v188, v[62:63], off offset:112
	global_load_dword v189, v[62:63], off offset:120
	global_load_dword v190, v[62:63], off offset:128
	global_load_dword v191, v[62:63], off offset:136
	global_load_dword v192, v[62:63], off offset:144
	global_load_dword v193, v[62:63], off offset:152
	global_load_dword v194, v[62:63], off offset:160
	global_load_dword v195, v[62:63], off offset:168
	global_load_dword v196, v[62:63], off offset:176
	global_load_dword v197, v[62:63], off offset:184
	global_load_dword v199, v[62:63], off offset:192
	global_load_dword v200, v[62:63], off offset:200
	global_load_dword v201, v[62:63], off offset:208
	global_load_dword v202, v[62:63], off offset:216
	global_load_dword v203, v[62:63], off offset:224
	global_load_dword v204, v[62:63], off offset:232
	global_load_dword v205, v[62:63], off offset:240
	global_load_dword v206, v[62:63], off offset:248
	s_nop 0
	s_waitcnt vmcnt(0) lgkmcnt(0)
	v_mul_f32_e32 v29, v59, v174
	ds_write_b32 v114, v29
	v_mov_b32_e32 v29, v97
	v_lshl_add_u64 v[62:63], s[58:59], 0, v[28:29]
	s_nop 0
	s_waitcnt vmcnt(0) lgkmcnt(0)
	v_mul_f32_e32 v29, v60, v175
	s_cbranch_execnz .LBB0_788

.LBB0_835:
	s_andn2_b64 vcc, exec, s[0:1]
	s_cbranch_vccnz .LBB0_609
	v_mov_b32_e32 v27, 0x20418
	v_lshlrev_b32_e32 v96, 2, v0
	v_add_u32_e32 v27, 0, v27
	ds_read2_b32 v[28:29], v27 offset1:1
	v_mov_b32_e32 v27, 0x20410
	s_waitcnt lgkmcnt(0)
	v_readfirstlane_b32 s0, v28
	v_add_u32_e32 v27, 0, v27
	v_readfirstlane_b32 s1, v29
	ds_read2_b32 v[28:29], v27 offset1:1
	s_add_u32 s2, s0, s47
	s_addc_u32 s8, s1, s45
	s_lshl_b64 s[14:15], s[60:61], 2
	s_waitcnt lgkmcnt(0)
	v_readfirstlane_b32 s0, v28
	v_readfirstlane_b32 s1, v29
	s_add_u32 s72, s0, s14
	s_mul_hi_i32 s14, s78, 0x2e8ba2e9
	s_addc_u32 s73, s1, s15
	s_lshr_b32 s15, s14, 31
	s_ashr_i32 s14, s14, 5
	s_add_i32 s15, s14, s15
	s_mul_i32 s14, s15, 0xffffff50
	s_add_i32 s14, s14, s78
	s_lshl_b32 s16, s14, 5
	s_lshl_b32 s14, s14, 4
	s_and_b32 s18, s16, 0xe0
	s_and_b32 s14, s14, 0xffffff80
	s_or_b32 s19, s14, s18
	s_add_i32 s14, s18, s14
	s_addk_i32 s14, 0xa80
	s_cmpk_lt_u32 s18, 0x80
	s_cselect_b32 s14, s19, s14
	s_lshl_b32 s58, s15, 6
	s_ashr_i32 s15, s14, 31
	s_lshl_b64 s[14:15], s[14:15], 2
	s_add_u32 s14, s2, s14
	s_addc_u32 s15, s8, s15
	v_or_b32_e32 v28, s58, v2
	v_lshl_add_u64 v[62:63], s[14:15], 0, v[96:97]
	v_mad_i64_i32 v[30:31], s[14:15], v28, s3, v[62:63]
	v_or_b32_e32 v27, 2, v28
	flat_load_dword v59, v[30:31]
	v_mad_i64_i32 v[30:31], s[14:15], v27, s3, v[62:63]
	v_or_b32_e32 v27, 4, v28
	flat_load_dword v60, v[30:31]
	v_mad_i64_i32 v[30:31], s[14:15], v27, s3, v[62:63]
	v_or_b32_e32 v27, 6, v28
	flat_load_dword v57, v[30:31]
	v_mad_i64_i32 v[30:31], s[14:15], v27, s3, v[62:63]
	v_or_b32_e32 v27, 8, v28
	flat_load_dword v58, v[30:31]
	v_mad_i64_i32 v[30:31], s[14:15], v27, s3, v[62:63]
	v_or_b32_e32 v27, 10, v28
	flat_load_dword v54, v[30:31]
	v_mad_i64_i32 v[30:31], s[14:15], v27, s3, v[62:63]
	v_or_b32_e32 v27, 12, v28
	flat_load_dword v56, v[30:31]
	v_mad_i64_i32 v[30:31], s[14:15], v27, s3, v[62:63]
	v_or_b32_e32 v27, 14, v28
	flat_load_dword v53, v[30:31]
	v_mad_i64_i32 v[30:31], s[14:15], v27, s3, v[62:63]
	v_or_b32_e32 v27, 16, v28
	flat_load_dword v55, v[30:31]
	v_mad_i64_i32 v[30:31], s[14:15], v27, s3, v[62:63]
	v_or_b32_e32 v27, 18, v28
	flat_load_dword v51, v[30:31]
	v_mad_i64_i32 v[30:31], s[14:15], v27, s3, v[62:63]
	v_or_b32_e32 v27, 20, v28
	flat_load_dword v52, v[30:31]
	v_mad_i64_i32 v[30:31], s[14:15], v27, s3, v[62:63]
	v_or_b32_e32 v27, 22, v28
	flat_load_dword v49, v[30:31]
	v_mad_i64_i32 v[30:31], s[14:15], v27, s3, v[62:63]
	v_or_b32_e32 v27, 24, v28
	flat_load_dword v50, v[30:31]
	v_mad_i64_i32 v[30:31], s[14:15], v27, s3, v[62:63]
	v_or_b32_e32 v27, 26, v28
	flat_load_dword v46, v[30:31]
	v_mad_i64_i32 v[30:31], s[14:15], v27, s3, v[62:63]
	v_or_b32_e32 v27, 28, v28
	flat_load_dword v48, v[30:31]
	v_mad_i64_i32 v[30:31], s[14:15], v27, s3, v[62:63]
	v_or_b32_e32 v27, 30, v28
	flat_load_dword v45, v[30:31]
	v_mad_i64_i32 v[30:31], s[14:15], v27, s3, v[62:63]
	v_or_b32_e32 v27, 32, v28
	flat_load_dword v47, v[30:31]
	v_mad_i64_i32 v[30:31], s[14:15], v27, s3, v[62:63]
	v_or_b32_e32 v27, 34, v28
	flat_load_dword v43, v[30:31]
	v_mad_i64_i32 v[30:31], s[14:15], v27, s3, v[62:63]
	v_or_b32_e32 v27, 36, v28
	flat_load_dword v44, v[30:31]
	v_mad_i64_i32 v[30:31], s[14:15], v27, s3, v[62:63]
	v_or_b32_e32 v27, 38, v28
	flat_load_dword v41, v[30:31]
	v_mad_i64_i32 v[30:31], s[14:15], v27, s3, v[62:63]
	v_or_b32_e32 v27, 40, v28
	flat_load_dword v42, v[30:31]
	v_mad_i64_i32 v[30:31], s[14:15], v27, s3, v[62:63]
	v_or_b32_e32 v27, 42, v28
	flat_load_dword v38, v[30:31]
	v_mad_i64_i32 v[30:31], s[14:15], v27, s3, v[62:63]
	v_or_b32_e32 v27, 44, v28
	flat_load_dword v40, v[30:31]
	v_mad_i64_i32 v[30:31], s[14:15], v27, s3, v[62:63]
	v_or_b32_e32 v27, 46, v28
	flat_load_dword v37, v[30:31]
	v_mad_i64_i32 v[30:31], s[14:15], v27, s3, v[62:63]
	v_or_b32_e32 v27, 48, v28
	flat_load_dword v39, v[30:31]
	v_mad_i64_i32 v[30:31], s[14:15], v27, s3, v[62:63]
	v_or_b32_e32 v27, 50, v28
	flat_load_dword v35, v[30:31]
	v_mad_i64_i32 v[30:31], s[14:15], v27, s3, v[62:63]
	v_or_b32_e32 v27, 52, v28
	flat_load_dword v36, v[30:31]
	v_mad_i64_i32 v[30:31], s[14:15], v27, s3, v[62:63]
	v_or_b32_e32 v27, 54, v28
	flat_load_dword v33, v[30:31]
	v_mad_i64_i32 v[30:31], s[14:15], v27, s3, v[62:63]
	v_or_b32_e32 v27, 56, v28
	flat_load_dword v34, v[30:31]
	v_mad_i64_i32 v[30:31], s[14:15], v27, s3, v[62:63]
	v_or_b32_e32 v27, 58, v28
	v_mad_i64_i32 v[64:65], s[14:15], v27, s3, v[62:63]
	v_or_b32_e32 v27, 60, v28
	v_or_b32_e32 v29, 62, v28
	flat_load_dword v31, v[30:31]
	s_cmp_lg_u64 s[0:1], 0
	flat_load_dword v32, v[64:65]
	v_mad_i64_i32 v[64:65], s[14:15], v27, s3, v[62:63]
	v_mad_i64_i32 v[62:63], s[14:15], v29, s3, v[62:63]
	flat_load_dword v27, v[64:65]
	flat_load_dword v30, v[62:63]
	s_cselect_b64 s[24:25], -1, 0
	s_cmp_eq_u64 s[0:1], 0
	s_cbranch_scc1 .LBB0_883
	v_ashrrev_i32_e32 v29, 31, v28
	v_lshl_add_u64 v[28:29], v[28:29], 2, s[72:73]
	global_load_dword v174, v[28:29], off
	global_load_dword v175, v[28:29], off offset:8
	global_load_dword v176, v[28:29], off offset:16
	global_load_dword v177, v[28:29], off offset:24
	global_load_dword v178, v[28:29], off offset:32
	global_load_dword v179, v[28:29], off offset:40
	global_load_dword v180, v[28:29], off offset:48
	global_load_dword v181, v[28:29], off offset:56
	global_load_dword v182, v[28:29], off offset:64
	global_load_dword v183, v[28:29], off offset:72
	global_load_dword v184, v[28:29], off offset:80
	global_load_dword v185, v[28:29], off offset:88
	global_load_dword v186, v[28:29], off offset:96
	global_load_dword v187, v[28:29], off offset:104
	global_load_dword v188, v[28:29], off offset:112
	global_load_dword v189, v[28:29], off offset:120
	global_load_dword v190, v[28:29], off offset:128
	global_load_dword v191, v[28:29], off offset:136
	global_load_dword v192, v[28:29], off offset:144
	global_load_dword v193, v[28:29], off offset:152
	global_load_dword v194, v[28:29], off offset:160
	global_load_dword v195, v[28:29], off offset:168
	global_load_dword v196, v[28:29], off offset:176
	global_load_dword v197, v[28:29], off offset:184
	global_load_dword v199, v[28:29], off offset:192
	global_load_dword v200, v[28:29], off offset:200
	global_load_dword v201, v[28:29], off offset:208
	global_load_dword v202, v[28:29], off offset:216
	global_load_dword v203, v[28:29], off offset:224
	global_load_dword v204, v[28:29], off offset:232
	global_load_dword v205, v[28:29], off offset:240
	global_load_dword v206, v[28:29], off offset:248
	s_nop 0
	s_ashr_i32 s59, s58, 31
	s_waitcnt vmcnt(0) lgkmcnt(0)
	v_mul_f32_e32 v28, v59, v174
	ds_write_b32 v114, v28
	v_lshl_add_u64 v[28:29], s[58:59], 0, v[2:3]
	v_lshl_add_u64 v[28:29], v[28:29], 2, s[72:73]
	s_nop 0
	s_waitcnt vmcnt(0) lgkmcnt(0)
	v_mul_f32_e32 v28, v60, v175
	s_cbranch_execnz .LBB0_839

.LBB0_839:
	v_add_u32_e32 v29, v1, v120
	ds_write_b32 v29, v28
	v_cndmask_b32_e64 v28, 0, 1, s[24:25]
	v_cmp_ne_u32_e64 s[0:1], 1, v28
	s_andn2_b64 vcc, exec, s[24:25]
	v_add_u32_e32 v28, v1, v121
	s_cbranch_vccnz .LBB0_884
	s_ashr_i32 s59, s58, 31
	s_waitcnt vmcnt(0) lgkmcnt(0)
	v_lshl_add_u64 v[60:61], s[58:59], 0, v[2:3]
	v_lshl_add_u64 v[60:61], v[60:61], 2, s[72:73]
	s_nop 0
	s_waitcnt vmcnt(0) lgkmcnt(0)
	v_mul_f32_e32 v29, v57, v176
	ds_write_b32 v28, v29
	s_nop 0
	s_waitcnt vmcnt(0) lgkmcnt(0)
	v_mul_f32_e32 v29, v58, v177
	s_cbranch_execnz .LBB0_842

.LBB0_842:
	v_add_u32_e32 v28, v1, v122
	ds_write_b32 v28, v29
	s_and_b64 vcc, exec, s[0:1]
	v_add_u32_e32 v28, v1, v123
	s_cbranch_vccnz .LBB0_885
	s_ashr_i32 s59, s58, 31
	s_waitcnt vmcnt(0) lgkmcnt(0)
	v_lshl_add_u64 v[58:59], s[58:59], 0, v[2:3]
	v_lshl_add_u64 v[58:59], v[58:59], 2, s[72:73]
	s_nop 0
	s_waitcnt vmcnt(0) lgkmcnt(0)
	v_mul_f32_e32 v29, v54, v178
	ds_write_b32 v28, v29
	s_nop 0
	s_waitcnt vmcnt(0) lgkmcnt(0)
	v_mul_f32_e32 v29, v56, v179
	s_cbranch_execnz .LBB0_845

.LBB0_845:
	v_add_u32_e32 v28, v1, v124
	ds_write_b32 v28, v29
	s_and_b64 vcc, exec, s[0:1]
	v_add_u32_e32 v28, v1, v125
	s_cbranch_vccnz .LBB0_886
	s_ashr_i32 s59, s58, 31
	s_waitcnt vmcnt(0) lgkmcnt(0)
	v_lshl_add_u64 v[56:57], s[58:59], 0, v[2:3]
	v_lshl_add_u64 v[56:57], v[56:57], 2, s[72:73]
	s_nop 0
	s_waitcnt vmcnt(0) lgkmcnt(0)
	v_mul_f32_e32 v29, v53, v180
	ds_write_b32 v28, v29
	s_nop 0
	s_waitcnt vmcnt(0) lgkmcnt(0)
	v_mul_f32_e32 v29, v55, v181
	s_cbranch_execnz .LBB0_848

.LBB0_848:
	v_add_u32_e32 v28, v1, v126
	ds_write_b32 v28, v29
	s_and_b64 vcc, exec, s[0:1]
	v_add_u32_e32 v28, v1, v127
	s_cbranch_vccnz .LBB0_887
	s_ashr_i32 s59, s58, 31
	s_waitcnt vmcnt(0) lgkmcnt(0)
	v_lshl_add_u64 v[54:55], s[58:59], 0, v[2:3]
	v_lshl_add_u64 v[54:55], v[54:55], 2, s[72:73]
	s_nop 0
	s_waitcnt vmcnt(0) lgkmcnt(0)
	v_mul_f32_e32 v29, v51, v182
	ds_write_b32 v28, v29
	s_nop 0
	s_waitcnt vmcnt(0) lgkmcnt(0)
	v_mul_f32_e32 v29, v52, v183
	s_cbranch_execnz .LBB0_851

.LBB0_851:
	v_add_u32_e32 v28, v1, v128
	ds_write_b32 v28, v29
	s_and_b64 vcc, exec, s[0:1]
	v_add_u32_e32 v28, v1, v129
	s_cbranch_vccnz .LBB0_888
	s_ashr_i32 s59, s58, 31
	s_waitcnt vmcnt(0) lgkmcnt(0)
	v_lshl_add_u64 v[52:53], s[58:59], 0, v[2:3]
	v_lshl_add_u64 v[52:53], v[52:53], 2, s[72:73]
	s_nop 0
	s_waitcnt vmcnt(0) lgkmcnt(0)
	v_mul_f32_e32 v29, v49, v184
	ds_write_b32 v28, v29
	s_nop 0
	s_waitcnt vmcnt(0) lgkmcnt(0)
	v_mul_f32_e32 v29, v50, v185
	s_cbranch_execnz .LBB0_854

.LBB0_854:
	v_add_u32_e32 v28, v1, v130
	ds_write_b32 v28, v29
	s_and_b64 vcc, exec, s[0:1]
	v_add_u32_e32 v28, v1, v131
	s_cbranch_vccnz .LBB0_889
	s_ashr_i32 s59, s58, 31
	s_waitcnt vmcnt(0) lgkmcnt(0)
	v_lshl_add_u64 v[50:51], s[58:59], 0, v[2:3]
	v_lshl_add_u64 v[50:51], v[50:51], 2, s[72:73]
	s_nop 0
	s_waitcnt vmcnt(0) lgkmcnt(0)
	v_mul_f32_e32 v29, v46, v186
	ds_write_b32 v28, v29
	s_nop 0
	s_waitcnt vmcnt(0) lgkmcnt(0)
	v_mul_f32_e32 v29, v48, v187
	s_cbranch_execnz .LBB0_857

.LBB0_857:
	v_add_u32_e32 v28, v1, v132
	ds_write_b32 v28, v29
	s_and_b64 vcc, exec, s[0:1]
	v_add_u32_e32 v28, v1, v133
	s_cbranch_vccnz .LBB0_890
	s_ashr_i32 s59, s58, 31
	s_waitcnt vmcnt(0) lgkmcnt(0)
	v_lshl_add_u64 v[48:49], s[58:59], 0, v[2:3]
	v_lshl_add_u64 v[48:49], v[48:49], 2, s[72:73]
	s_nop 0
	s_waitcnt vmcnt(0) lgkmcnt(0)
	v_mul_f32_e32 v29, v45, v188
	ds_write_b32 v28, v29
	s_nop 0
	s_waitcnt vmcnt(0) lgkmcnt(0)
	v_mul_f32_e32 v29, v47, v189
	s_cbranch_execnz .LBB0_860

.LBB0_860:
	v_add_u32_e32 v28, v1, v134
	ds_write_b32 v28, v29
	s_and_b64 vcc, exec, s[0:1]
	v_add_u32_e32 v28, v1, v135
	s_cbranch_vccnz .LBB0_891
	s_ashr_i32 s59, s58, 31
	s_waitcnt vmcnt(0) lgkmcnt(0)
	v_lshl_add_u64 v[46:47], s[58:59], 0, v[2:3]
	v_lshl_add_u64 v[46:47], v[46:47], 2, s[72:73]
	s_nop 0
	s_waitcnt vmcnt(0) lgkmcnt(0)
	v_mul_f32_e32 v29, v43, v190
	ds_write_b32 v28, v29
	s_nop 0
	s_waitcnt vmcnt(0) lgkmcnt(0)
	v_mul_f32_e32 v29, v44, v191
	s_cbranch_execnz .LBB0_863

.LBB0_863:
	v_add_u32_e32 v28, v1, v136
	ds_write_b32 v28, v29
	s_and_b64 vcc, exec, s[0:1]
	v_add_u32_e32 v28, v1, v137
	s_cbranch_vccnz .LBB0_892
	s_ashr_i32 s59, s58, 31
	s_waitcnt vmcnt(0) lgkmcnt(0)
	v_lshl_add_u64 v[44:45], s[58:59], 0, v[2:3]
	v_lshl_add_u64 v[44:45], v[44:45], 2, s[72:73]
	s_nop 0
	s_waitcnt vmcnt(0) lgkmcnt(0)
	v_mul_f32_e32 v29, v41, v192
	ds_write_b32 v28, v29
	s_nop 0
	s_waitcnt vmcnt(0) lgkmcnt(0)
	v_mul_f32_e32 v29, v42, v193
	s_cbranch_execnz .LBB0_866

.LBB0_866:
	v_add_u32_e32 v28, v1, v138
	ds_write_b32 v28, v29
	s_and_b64 vcc, exec, s[0:1]
	v_add_u32_e32 v28, v1, v139
	s_cbranch_vccnz .LBB0_893
	s_ashr_i32 s59, s58, 31
	s_waitcnt vmcnt(0) lgkmcnt(0)
	v_lshl_add_u64 v[42:43], s[58:59], 0, v[2:3]
	v_lshl_add_u64 v[42:43], v[42:43], 2, s[72:73]
	s_nop 0
	s_waitcnt vmcnt(0) lgkmcnt(0)
	v_mul_f32_e32 v29, v38, v194
	ds_write_b32 v28, v29
	s_nop 0
	s_waitcnt vmcnt(0) lgkmcnt(0)
	v_mul_f32_e32 v29, v40, v195
	s_cbranch_execnz .LBB0_869

.LBB0_869:
	v_add_u32_e32 v28, v1, v140
	ds_write_b32 v28, v29
	s_and_b64 vcc, exec, s[0:1]
	v_add_u32_e32 v28, v1, v141
	s_cbranch_vccnz .LBB0_894
	s_ashr_i32 s59, s58, 31
	s_waitcnt vmcnt(0) lgkmcnt(0)
	v_lshl_add_u64 v[40:41], s[58:59], 0, v[2:3]
	v_lshl_add_u64 v[40:41], v[40:41], 2, s[72:73]
	s_nop 0
	s_waitcnt vmcnt(0) lgkmcnt(0)
	v_mul_f32_e32 v29, v37, v196
	ds_write_b32 v28, v29
	s_nop 0
	s_waitcnt vmcnt(0) lgkmcnt(0)
	v_mul_f32_e32 v29, v39, v197
	s_cbranch_execnz .LBB0_872

.LBB0_872:
	v_add_u32_e32 v28, v1, v142
	ds_write_b32 v28, v29
	s_and_b64 vcc, exec, s[0:1]
	v_add_u32_e32 v28, v1, v143
	s_cbranch_vccnz .LBB0_895
	s_ashr_i32 s59, s58, 31
	s_waitcnt vmcnt(0) lgkmcnt(0)
	v_lshl_add_u64 v[38:39], s[58:59], 0, v[2:3]
	v_lshl_add_u64 v[38:39], v[38:39], 2, s[72:73]
	s_nop 0
	s_waitcnt vmcnt(0) lgkmcnt(0)
	v_mul_f32_e32 v29, v35, v199
	ds_write_b32 v28, v29
	s_nop 0
	s_waitcnt vmcnt(0) lgkmcnt(0)
	v_mul_f32_e32 v29, v36, v200
	s_cbranch_execnz .LBB0_875

.LBB0_875:
	v_add_u32_e32 v28, v1, v144
	s_and_b64 vcc, exec, s[0:1]
	ds_write_b32 v28, v29
	s_cbranch_vccnz .LBB0_896
	s_ashr_i32 s59, s58, 31
	s_waitcnt vmcnt(0) lgkmcnt(0)
	v_lshl_add_u64 v[36:37], s[58:59], 0, v[2:3]
	v_lshl_add_u64 v[36:37], v[36:37], 2, s[72:73]
	s_nop 0
	s_waitcnt vmcnt(0) lgkmcnt(0)
	v_mul_f32_e32 v29, v33, v201
	ds_write_b32 v28, v29 offset:264
	s_nop 0
	s_waitcnt vmcnt(0) lgkmcnt(0)
	v_mul_f32_e32 v29, v34, v202
	s_cbranch_execnz .LBB0_878

.LBB0_878:
	s_and_b64 vcc, exec, s[0:1]
	ds_write_b32 v28, v29 offset:528
	s_cbranch_vccnz .LBB0_897
	s_ashr_i32 s59, s58, 31
	s_waitcnt vmcnt(0) lgkmcnt(0)
	v_lshl_add_u64 v[34:35], s[58:59], 0, v[2:3]
	v_lshl_add_u64 v[34:35], v[34:35], 2, s[72:73]
	s_nop 0
	s_waitcnt vmcnt(0) lgkmcnt(0)
	v_mul_f32_e32 v29, v31, v203
	ds_write_b32 v28, v29 offset:792
	s_nop 0
	s_waitcnt vmcnt(0) lgkmcnt(0)
	v_mul_f32_e32 v29, v32, v204
	s_cbranch_execnz .LBB0_881

.LBB0_881:
	s_and_b64 vcc, exec, s[0:1]
	ds_write_b32 v28, v29 offset:1056
	s_cbranch_vccnz .LBB0_898
	s_ashr_i32 s59, s58, 31
	s_waitcnt vmcnt(0) lgkmcnt(0)
	v_lshl_add_u64 v[32:33], s[58:59], 0, v[2:3]
	v_lshl_add_u64 v[32:33], v[32:33], 2, s[72:73]
	s_nop 0
	s_waitcnt vmcnt(0) lgkmcnt(0)
	v_mul_f32_e32 v29, v27, v205
	ds_write_b32 v28, v29 offset:1320
	s_nop 0
	s_waitcnt vmcnt(0) lgkmcnt(0)
	v_mul_f32_e32 v29, v30, v206
	s_cbranch_execnz .LBB0_608
	s_branch .LBB0_899

.LBB0_971:
	v_mov_b32_e32 v3, 0x204c8
	s_ashr_i32 s0, s18, 31
	v_add_u32_e32 v3, 0, v3
	ds_read2_b32 v[4:5], v3 offset1:1
	s_lshr_b32 s0, s0, 24
	v_mov_b32_e32 v3, 0x204b8
	s_add_i32 s0, s18, s0
	s_ashr_i32 s4, s0, 8
	v_add_u32_e32 v3, 0, v3
	s_and_b32 s0, s0, 0xffffff00
	s_waitcnt lgkmcnt(0)
	v_readfirstlane_b32 s6, v4
	v_readfirstlane_b32 s7, v5
	s_ashr_i32 s5, s4, 31
	ds_read2_b32 v[4:5], v3 offset1:1
	s_sub_i32 s2, s18, s0
	s_lshl_b64 s[0:1], s[4:5], 21
	s_add_u32 s14, s6, s0
	s_addc_u32 s24, s7, s1
	s_lshl_b32 s6, s4, 10
	s_ashr_i32 s7, s6, 31
	s_waitcnt lgkmcnt(0)
	v_readfirstlane_b32 s0, v4
	s_lshl_b64 s[6:7], s[6:7], 2
	v_readfirstlane_b32 s1, v5
	s_add_u32 s48, s0, s6
	s_addc_u32 s49, s1, s7
	s_ashr_i32 s6, s2, 31
	s_lshr_b32 s6, s6, 28
	s_add_i32 s2, s2, s6
	s_ashr_i32 s2, s2, 4
	s_lshl_b32 s19, s2, 9
	s_lshl_b32 s6, s4, 13
	s_add_i32 s19, s19, s6
	s_sub_i32 s6, s8, s19
	s_ashr_i32 s20, s6, 2
	s_and_b32 s7, s9, 0xc0
	s_andn2_b32 s20, s20, 31
	s_add_i32 s20, s20, s7
	s_cmpk_lt_i32 s6, 0x100
	s_cselect_b32 s20, s20, s6
	s_lshl_b32 s6, s2, 6
	s_ashr_i32 s21, s20, 31
	v_or_b32_e32 v4, s6, v0
	s_lshl_b64 s[20:21], s[20:21], 2
	s_add_u32 s20, s14, s20
	v_or_b32_e32 v50, 54, v4
	s_addc_u32 s21, s24, s21
	v_ashrrev_i32_e32 v5, 31, v4
	v_ashrrev_i32_e32 v51, 31, v50
	v_lshl_add_u64 v[6:7], s[20:21], 0, v[96:97]
	v_lshlrev_b64 v[20:21], 11, v[4:5]
	v_lshlrev_b64 v[50:51], 11, v[50:51]
	v_lshl_add_u64 v[20:21], v[6:7], 0, v[20:21]
	v_lshl_add_u64 v[50:51], v[6:7], 0, v[50:51]
	flat_load_dword v47, v[20:21]
	flat_load_dword v22, v[50:51]
	v_or_b32_e32 v20, 2, v4
	v_or_b32_e32 v50, 56, v4
	v_ashrrev_i32_e32 v21, 31, v20
	v_ashrrev_i32_e32 v51, 31, v50
	v_lshlrev_b64 v[20:21], 11, v[20:21]
	v_lshlrev_b64 v[50:51], 11, v[50:51]
	v_lshl_add_u64 v[20:21], v[6:7], 0, v[20:21]
	v_lshl_add_u64 v[50:51], v[6:7], 0, v[50:51]
	flat_load_dword v48, v[20:21]
	flat_load_dword v19, v[50:51]
	v_or_b32_e32 v20, 4, v4
	v_ashrrev_i32_e32 v21, 31, v20
	v_lshlrev_b64 v[20:21], 11, v[20:21]
	v_lshl_add_u64 v[20:21], v[6:7], 0, v[20:21]
	flat_load_dword v45, v[20:21]
	v_or_b32_e32 v20, 6, v4
	v_ashrrev_i32_e32 v21, 31, v20
	v_lshlrev_b64 v[20:21], 11, v[20:21]
	v_lshl_add_u64 v[20:21], v[6:7], 0, v[20:21]
	flat_load_dword v46, v[20:21]
	v_or_b32_e32 v20, 8, v4
	v_ashrrev_i32_e32 v21, 31, v20
	v_lshlrev_b64 v[20:21], 11, v[20:21]
	v_lshl_add_u64 v[20:21], v[6:7], 0, v[20:21]
	flat_load_dword v42, v[20:21]
	v_or_b32_e32 v20, 10, v4
	v_ashrrev_i32_e32 v21, 31, v20
	v_lshlrev_b64 v[20:21], 11, v[20:21]
	v_lshl_add_u64 v[20:21], v[6:7], 0, v[20:21]
	flat_load_dword v43, v[20:21]
	v_or_b32_e32 v20, 12, v4
	v_ashrrev_i32_e32 v21, 31, v20
	v_lshlrev_b64 v[20:21], 11, v[20:21]
	v_lshl_add_u64 v[20:21], v[6:7], 0, v[20:21]
	flat_load_dword v39, v[20:21]
	v_or_b32_e32 v20, 14, v4
	v_ashrrev_i32_e32 v21, 31, v20
	v_lshlrev_b64 v[20:21], 11, v[20:21]
	v_lshl_add_u64 v[20:21], v[6:7], 0, v[20:21]
	flat_load_dword v44, v[20:21]
	v_or_b32_e32 v20, 16, v4
	v_ashrrev_i32_e32 v21, 31, v20
	v_lshlrev_b64 v[20:21], 11, v[20:21]
	v_lshl_add_u64 v[20:21], v[6:7], 0, v[20:21]
	flat_load_dword v40, v[20:21]
	v_or_b32_e32 v20, 18, v4
	v_ashrrev_i32_e32 v21, 31, v20
	v_lshlrev_b64 v[20:21], 11, v[20:21]
	v_lshl_add_u64 v[20:21], v[6:7], 0, v[20:21]
	flat_load_dword v41, v[20:21]
	v_or_b32_e32 v20, 20, v4
	v_ashrrev_i32_e32 v21, 31, v20
	v_lshlrev_b64 v[20:21], 11, v[20:21]
	v_lshl_add_u64 v[20:21], v[6:7], 0, v[20:21]
	flat_load_dword v37, v[20:21]
	v_or_b32_e32 v20, 22, v4
	v_ashrrev_i32_e32 v21, 31, v20
	v_lshlrev_b64 v[20:21], 11, v[20:21]
	v_lshl_add_u64 v[20:21], v[6:7], 0, v[20:21]
	flat_load_dword v38, v[20:21]
	v_or_b32_e32 v20, 24, v4
	v_ashrrev_i32_e32 v21, 31, v20
	v_lshlrev_b64 v[20:21], 11, v[20:21]
	v_lshl_add_u64 v[20:21], v[6:7], 0, v[20:21]
	flat_load_dword v34, v[20:21]
	v_or_b32_e32 v20, 26, v4
	v_ashrrev_i32_e32 v21, 31, v20
	v_lshlrev_b64 v[20:21], 11, v[20:21]
	v_lshl_add_u64 v[20:21], v[6:7], 0, v[20:21]
	flat_load_dword v35, v[20:21]
	v_or_b32_e32 v20, 28, v4
	v_ashrrev_i32_e32 v21, 31, v20
	v_lshlrev_b64 v[20:21], 11, v[20:21]
	v_lshl_add_u64 v[20:21], v[6:7], 0, v[20:21]
	flat_load_dword v31, v[20:21]
	v_or_b32_e32 v20, 30, v4
	v_ashrrev_i32_e32 v21, 31, v20
	v_lshlrev_b64 v[20:21], 11, v[20:21]
	v_lshl_add_u64 v[20:21], v[6:7], 0, v[20:21]
	flat_load_dword v36, v[20:21]
	v_or_b32_e32 v20, 32, v4
	v_ashrrev_i32_e32 v21, 31, v20
	v_lshlrev_b64 v[20:21], 11, v[20:21]
	v_lshl_add_u64 v[20:21], v[6:7], 0, v[20:21]
	flat_load_dword v32, v[20:21]
	v_or_b32_e32 v20, 34, v4
	v_ashrrev_i32_e32 v21, 31, v20
	v_lshlrev_b64 v[20:21], 11, v[20:21]
	v_lshl_add_u64 v[20:21], v[6:7], 0, v[20:21]
	flat_load_dword v33, v[20:21]
	v_or_b32_e32 v20, 36, v4
	v_ashrrev_i32_e32 v21, 31, v20
	v_lshlrev_b64 v[20:21], 11, v[20:21]
	v_lshl_add_u64 v[20:21], v[6:7], 0, v[20:21]
	flat_load_dword v29, v[20:21]
	v_or_b32_e32 v20, 38, v4
	v_ashrrev_i32_e32 v21, 31, v20
	v_lshlrev_b64 v[20:21], 11, v[20:21]
	v_lshl_add_u64 v[20:21], v[6:7], 0, v[20:21]
	flat_load_dword v30, v[20:21]
	v_or_b32_e32 v20, 40, v4
	v_ashrrev_i32_e32 v21, 31, v20
	v_lshlrev_b64 v[20:21], 11, v[20:21]
	v_lshl_add_u64 v[20:21], v[6:7], 0, v[20:21]
	flat_load_dword v26, v[20:21]
	v_or_b32_e32 v20, 42, v4
	v_ashrrev_i32_e32 v21, 31, v20
	v_lshlrev_b64 v[20:21], 11, v[20:21]
	v_lshl_add_u64 v[20:21], v[6:7], 0, v[20:21]
	flat_load_dword v27, v[20:21]
	v_or_b32_e32 v20, 44, v4
	v_ashrrev_i32_e32 v21, 31, v20
	v_lshlrev_b64 v[20:21], 11, v[20:21]
	v_lshl_add_u64 v[20:21], v[6:7], 0, v[20:21]
	flat_load_dword v23, v[20:21]
	v_or_b32_e32 v20, 46, v4
	v_ashrrev_i32_e32 v21, 31, v20
	v_lshlrev_b64 v[20:21], 11, v[20:21]
	v_lshl_add_u64 v[20:21], v[6:7], 0, v[20:21]
	flat_load_dword v28, v[20:21]
	v_or_b32_e32 v20, 48, v4
	v_ashrrev_i32_e32 v21, 31, v20
	v_lshlrev_b64 v[20:21], 11, v[20:21]
	v_lshl_add_u64 v[20:21], v[6:7], 0, v[20:21]
	flat_load_dword v24, v[20:21]
	v_or_b32_e32 v20, 50, v4
	v_ashrrev_i32_e32 v21, 31, v20
	v_lshlrev_b64 v[20:21], 11, v[20:21]
	v_lshl_add_u64 v[20:21], v[6:7], 0, v[20:21]
	flat_load_dword v25, v[20:21]
	v_or_b32_e32 v20, 52, v4
	v_or_b32_e32 v50, 58, v4
	v_ashrrev_i32_e32 v21, 31, v20
	v_ashrrev_i32_e32 v51, 31, v50
	v_lshlrev_b64 v[20:21], 11, v[20:21]
	v_lshlrev_b64 v[50:51], 11, v[50:51]
	v_lshl_add_u64 v[20:21], v[6:7], 0, v[20:21]
	v_lshl_add_u64 v[50:51], v[6:7], 0, v[50:51]
	flat_load_dword v21, v[20:21]
	s_cmp_lg_u64 s[0:1], 0
	flat_load_dword v20, v[50:51]
	v_or_b32_e32 v50, 60, v4
	v_ashrrev_i32_e32 v51, 31, v50
	v_lshlrev_b64 v[50:51], 11, v[50:51]
	v_lshl_add_u64 v[50:51], v[6:7], 0, v[50:51]
	flat_load_dword v3, v[50:51]
	v_or_b32_e32 v50, 62, v4
	v_ashrrev_i32_e32 v51, 31, v50
	v_lshlrev_b64 v[50:51], 11, v[50:51]
	v_lshl_add_u64 v[6:7], v[6:7], 0, v[50:51]
	flat_load_dword v6, v[6:7]
	s_cselect_b64 s[24:25], -1, 0
	s_cmp_eq_u64 s[0:1], 0
	s_cbranch_scc1 .LBB0_1018
	v_lshl_add_u64 v[4:5], v[4:5], 2, s[48:49]
	global_load_dword v174, v[4:5], off
	global_load_dword v175, v[4:5], off offset:8
	global_load_dword v176, v[4:5], off offset:16
	global_load_dword v177, v[4:5], off offset:24
	global_load_dword v178, v[4:5], off offset:32
	global_load_dword v179, v[4:5], off offset:40
	global_load_dword v180, v[4:5], off offset:48
	global_load_dword v181, v[4:5], off offset:56
	global_load_dword v182, v[4:5], off offset:64
	global_load_dword v183, v[4:5], off offset:72
	global_load_dword v184, v[4:5], off offset:80
	global_load_dword v185, v[4:5], off offset:88
	global_load_dword v186, v[4:5], off offset:96
	global_load_dword v187, v[4:5], off offset:104
	global_load_dword v188, v[4:5], off offset:112
	global_load_dword v189, v[4:5], off offset:120
	global_load_dword v190, v[4:5], off offset:128
	global_load_dword v191, v[4:5], off offset:136
	global_load_dword v192, v[4:5], off offset:144
	global_load_dword v193, v[4:5], off offset:152
	global_load_dword v194, v[4:5], off offset:160
	global_load_dword v195, v[4:5], off offset:168
	global_load_dword v196, v[4:5], off offset:176
	global_load_dword v197, v[4:5], off offset:184
	global_load_dword v199, v[4:5], off offset:192
	global_load_dword v200, v[4:5], off offset:200
	global_load_dword v201, v[4:5], off offset:208
	global_load_dword v202, v[4:5], off offset:216
	global_load_dword v203, v[4:5], off offset:224
	global_load_dword v204, v[4:5], off offset:232
	global_load_dword v205, v[4:5], off offset:240
	global_load_dword v206, v[4:5], off offset:248
	s_nop 0
	s_ashr_i32 s7, s6, 31
	s_waitcnt vmcnt(0) lgkmcnt(0)
	v_mul_f32_e32 v4, v47, v174
	ds_write_b32 v14, v4
	v_lshl_add_u64 v[4:5], s[6:7], 0, v[0:1]
	v_lshl_add_u64 v[4:5], v[4:5], 2, s[48:49]
	s_nop 0
	s_waitcnt vmcnt(0) lgkmcnt(0)
	v_mul_f32_e32 v4, v48, v175
	s_cbranch_execnz .LBB0_974

.LBB0_974:
	ds_write_b32 v10, v4
	v_cndmask_b32_e64 v4, 0, 1, s[24:25]
	v_cmp_ne_u32_e64 s[0:1], 1, v4
	s_andn2_b64 vcc, exec, s[24:25]
	s_cbranch_vccnz .LBB0_1019
	s_ashr_i32 s7, s6, 31
	v_lshl_add_u64 v[4:5], s[6:7], 0, v[0:1]
	v_lshl_add_u64 v[4:5], v[4:5], 2, s[48:49]
	s_nop 0
	s_waitcnt vmcnt(0) lgkmcnt(0)
	v_mul_f32_e32 v7, v45, v176
	ds_write_b32 v15, v7
	s_nop 0
	s_waitcnt vmcnt(0) lgkmcnt(0)
	v_mul_f32_e32 v4, v46, v177
	s_cbranch_execnz .LBB0_977

.LBB0_977:
	s_and_b64 vcc, exec, s[0:1]
	ds_write_b32 v11, v4
	s_cbranch_vccnz .LBB0_1020
	s_ashr_i32 s7, s6, 31
	v_lshl_add_u64 v[4:5], s[6:7], 0, v[0:1]
	v_lshl_add_u64 v[4:5], v[4:5], 2, s[48:49]
	s_nop 0
	s_waitcnt vmcnt(0) lgkmcnt(0)
	v_mul_f32_e32 v7, v42, v178
	ds_write_b32 v16, v7
	s_nop 0
	s_waitcnt vmcnt(0) lgkmcnt(0)
	v_mul_f32_e32 v4, v43, v179
	s_cbranch_execnz .LBB0_980

.LBB0_980:
	s_and_b64 vcc, exec, s[0:1]
	ds_write_b32 v12, v4
	s_cbranch_vccnz .LBB0_1021
	s_ashr_i32 s7, s6, 31
	v_lshl_add_u64 v[4:5], s[6:7], 0, v[0:1]
	v_lshl_add_u64 v[4:5], v[4:5], 2, s[48:49]
	s_nop 0
	s_waitcnt vmcnt(0) lgkmcnt(0)
	v_mul_f32_e32 v7, v39, v180
	ds_write_b32 v17, v7
	s_nop 0
	s_waitcnt vmcnt(0) lgkmcnt(0)
	v_mul_f32_e32 v4, v44, v181
	s_cbranch_execnz .LBB0_983

.LBB0_983:
	s_and_b64 vcc, exec, s[0:1]
	ds_write_b32 v13, v4
	s_cbranch_vccnz .LBB0_1022
	s_ashr_i32 s7, s6, 31
	v_lshl_add_u64 v[4:5], s[6:7], 0, v[0:1]
	v_lshl_add_u64 v[4:5], v[4:5], 2, s[48:49]
	s_nop 0
	s_waitcnt vmcnt(0) lgkmcnt(0)
	v_mul_f32_e32 v7, v40, v182
	ds_write_b32 v18, v7
	s_nop 0
	s_waitcnt vmcnt(0) lgkmcnt(0)
	v_mul_f32_e32 v4, v41, v183
	s_cbranch_execnz .LBB0_986

.LBB0_986:
	s_and_b64 vcc, exec, s[0:1]
	ds_write_b32 v18, v4 offset:264
	s_cbranch_vccnz .LBB0_1023
	s_ashr_i32 s7, s6, 31
	v_lshl_add_u64 v[4:5], s[6:7], 0, v[0:1]
	v_lshl_add_u64 v[4:5], v[4:5], 2, s[48:49]
	s_nop 0
	s_waitcnt vmcnt(0) lgkmcnt(0)
	v_mul_f32_e32 v7, v37, v184
	ds_write_b32 v18, v7 offset:528
	s_nop 0
	s_waitcnt vmcnt(0) lgkmcnt(0)
	v_mul_f32_e32 v4, v38, v185
	s_cbranch_execnz .LBB0_989

.LBB0_989:
	s_and_b64 vcc, exec, s[0:1]
	ds_write_b32 v18, v4 offset:792
	s_cbranch_vccnz .LBB0_1024
	s_ashr_i32 s7, s6, 31
	v_lshl_add_u64 v[4:5], s[6:7], 0, v[0:1]
	v_lshl_add_u64 v[4:5], v[4:5], 2, s[48:49]
	s_nop 0
	s_waitcnt vmcnt(0) lgkmcnt(0)
	v_mul_f32_e32 v7, v34, v186
	ds_write_b32 v18, v7 offset:1056
	s_nop 0
	s_waitcnt vmcnt(0) lgkmcnt(0)
	v_mul_f32_e32 v4, v35, v187
	s_cbranch_execnz .LBB0_992

.LBB0_992:
	s_and_b64 vcc, exec, s[0:1]
	ds_write_b32 v18, v4 offset:1320
	s_cbranch_vccnz .LBB0_1025
	s_ashr_i32 s7, s6, 31
	v_lshl_add_u64 v[4:5], s[6:7], 0, v[0:1]
	v_lshl_add_u64 v[4:5], v[4:5], 2, s[48:49]
	s_nop 0
	s_waitcnt vmcnt(0) lgkmcnt(0)
	v_mul_f32_e32 v7, v31, v188
	ds_write_b32 v18, v7 offset:1584
	s_nop 0
	s_waitcnt vmcnt(0) lgkmcnt(0)
	v_mul_f32_e32 v4, v36, v189
	s_cbranch_execnz .LBB0_995

.LBB0_995:
	s_and_b64 vcc, exec, s[0:1]
	ds_write_b32 v18, v4 offset:1848
	s_cbranch_vccnz .LBB0_1026
	s_ashr_i32 s7, s6, 31
	v_lshl_add_u64 v[4:5], s[6:7], 0, v[0:1]
	v_lshl_add_u64 v[4:5], v[4:5], 2, s[48:49]
	s_nop 0
	s_waitcnt vmcnt(0) lgkmcnt(0)
	v_mul_f32_e32 v7, v32, v190
	ds_write_b32 v18, v7 offset:2112
	s_nop 0
	s_waitcnt vmcnt(0) lgkmcnt(0)
	v_mul_f32_e32 v4, v33, v191
	s_cbranch_execnz .LBB0_998

.LBB0_998:
	s_and_b64 vcc, exec, s[0:1]
	ds_write_b32 v18, v4 offset:2376
	s_cbranch_vccnz .LBB0_1027
	s_ashr_i32 s7, s6, 31
	v_lshl_add_u64 v[4:5], s[6:7], 0, v[0:1]
	v_lshl_add_u64 v[4:5], v[4:5], 2, s[48:49]
	s_nop 0
	s_waitcnt vmcnt(0) lgkmcnt(0)
	v_mul_f32_e32 v7, v29, v192
	ds_write_b32 v18, v7 offset:2640
	s_nop 0
	s_waitcnt vmcnt(0) lgkmcnt(0)
	v_mul_f32_e32 v4, v30, v193
	s_cbranch_execnz .LBB0_1001

.LBB0_1001:
	s_and_b64 vcc, exec, s[0:1]
	ds_write_b32 v18, v4 offset:2904
	s_cbranch_vccnz .LBB0_1028
	s_ashr_i32 s7, s6, 31
	v_lshl_add_u64 v[4:5], s[6:7], 0, v[0:1]
	v_lshl_add_u64 v[4:5], v[4:5], 2, s[48:49]
	s_nop 0
	s_waitcnt vmcnt(0) lgkmcnt(0)
	v_mul_f32_e32 v7, v26, v194
	ds_write_b32 v18, v7 offset:3168
	s_nop 0
	s_waitcnt vmcnt(0) lgkmcnt(0)
	v_mul_f32_e32 v4, v27, v195
	s_cbranch_execnz .LBB0_1004

.LBB0_1004:
	s_and_b64 vcc, exec, s[0:1]
	ds_write_b32 v18, v4 offset:3432
	s_cbranch_vccnz .LBB0_1029
	s_ashr_i32 s7, s6, 31
	v_lshl_add_u64 v[4:5], s[6:7], 0, v[0:1]
	v_lshl_add_u64 v[4:5], v[4:5], 2, s[48:49]
	s_nop 0
	s_waitcnt vmcnt(0) lgkmcnt(0)
	v_mul_f32_e32 v7, v23, v196
	ds_write_b32 v18, v7 offset:3696
	s_nop 0
	s_waitcnt vmcnt(0) lgkmcnt(0)
	v_mul_f32_e32 v4, v28, v197
	s_cbranch_execnz .LBB0_1007

.LBB0_1007:
	s_and_b64 vcc, exec, s[0:1]
	ds_write_b32 v18, v4 offset:3960
	s_cbranch_vccnz .LBB0_1030
	s_ashr_i32 s7, s6, 31
	v_lshl_add_u64 v[4:5], s[6:7], 0, v[0:1]
	v_lshl_add_u64 v[4:5], v[4:5], 2, s[48:49]
	s_nop 0
	s_waitcnt vmcnt(0) lgkmcnt(0)
	v_mul_f32_e32 v7, v24, v199
	ds_write_b32 v18, v7 offset:4224
	s_nop 0
	s_waitcnt vmcnt(0) lgkmcnt(0)
	v_mul_f32_e32 v4, v25, v200
	s_cbranch_execnz .LBB0_1010

.LBB0_1010:
	s_and_b64 vcc, exec, s[0:1]
	ds_write_b32 v18, v4 offset:4488
	s_cbranch_vccnz .LBB0_1031
	s_ashr_i32 s7, s6, 31
	v_lshl_add_u64 v[4:5], s[6:7], 0, v[0:1]
	v_lshl_add_u64 v[4:5], v[4:5], 2, s[48:49]
	s_nop 0
	s_waitcnt vmcnt(0) lgkmcnt(0)
	v_mul_f32_e32 v7, v21, v201
	ds_write_b32 v18, v7 offset:4752
	s_nop 0
	s_waitcnt vmcnt(0) lgkmcnt(0)
	v_mul_f32_e32 v4, v22, v202
	s_cbranch_execnz .LBB0_1013

.LBB0_1013:
	s_and_b64 vcc, exec, s[0:1]
	ds_write_b32 v18, v4 offset:5016
	s_cbranch_vccnz .LBB0_1032
	s_ashr_i32 s7, s6, 31
	v_lshl_add_u64 v[4:5], s[6:7], 0, v[0:1]
	v_lshl_add_u64 v[4:5], v[4:5], 2, s[48:49]
	s_nop 0
	s_waitcnt vmcnt(0) lgkmcnt(0)
	v_mul_f32_e32 v7, v19, v203
	ds_write_b32 v18, v7 offset:5280
	s_nop 0
	s_waitcnt vmcnt(0) lgkmcnt(0)
	v_mul_f32_e32 v4, v20, v204
	s_cbranch_execnz .LBB0_1016

.LBB0_1016:
	s_and_b64 vcc, exec, s[0:1]
	ds_write_b32 v18, v4 offset:5544
	s_cbranch_vccnz .LBB0_1033
	s_ashr_i32 s7, s6, 31
	v_lshl_add_u64 v[4:5], s[6:7], 0, v[0:1]
	v_lshl_add_u64 v[4:5], v[4:5], 2, s[48:49]
	s_nop 0
	s_waitcnt vmcnt(0) lgkmcnt(0)
	v_mul_f32_e32 v7, v3, v205
	ds_write_b32 v18, v7 offset:5808
	s_nop 0
	s_waitcnt vmcnt(0) lgkmcnt(0)
	v_mul_f32_e32 v4, v6, v206
	s_cbranch_execnz .LBB0_970
	s_branch .LBB0_1034

.LBB0_1055:
	s_andn2_b64 vcc, exec, s[0:1]
	s_cbranch_vccnz .LBB0_1105
	v_mov_b32_e32 v25, 0x204c0
	s_add_i32 s15, s46, 0xffffd100
	v_add_u32_e32 v25, 0, v25
	ds_read2_b32 v[28:29], v25 offset1:1
	s_lshl_b32 s2, s15, 6
	s_lshl_b32 s6, s15, 3
	s_and_b32 s2, s2, 0xc0
	s_and_b32 s7, s6, 32
	s_or_b32 s2, s2, s7
	s_waitcnt lgkmcnt(0)
	v_readfirstlane_b32 s0, v28
	s_and_b32 s16, s6, 0x3c0
	s_lshl_b32 s2, s2, 2
	v_readfirstlane_b32 s1, v29
	s_add_u32 s0, s0, s2
	v_or_b32_e32 v29, s16, v2
	s_addc_u32 s1, s1, 0
	v_lshlrev_b32_e32 v96, 2, v0
	v_lshl_add_u64 v[30:31], s[0:1], 0, v[96:97]
	v_lshlrev_b32_e32 v96, 10, v29
	v_lshl_add_u64 v[30:31], v[30:31], 0, v[96:97]
	s_movk_i32 s0, 0x1000
	v_add_co_u32_e32 v32, vcc, s0, v30
	s_movk_i32 s0, 0x3000
	s_nop 0
	v_addc_co_u32_e32 v33, vcc, 0, v31, vcc
	v_add_co_u32_e32 v34, vcc, s96, v30
	v_mov_b32_e32 v61, 0x204b0
	s_nop 0
	v_addc_co_u32_e32 v35, vcc, 0, v31, vcc
	v_add_co_u32_e32 v36, vcc, s0, v30
	s_movk_i32 s0, 0x4000
	s_nop 0
	v_addc_co_u32_e32 v37, vcc, 0, v31, vcc
	flat_load_dword v59, v[30:31]
	flat_load_dword v60, v[30:31] offset:2048
	flat_load_dword v57, v[32:33]
	flat_load_dword v58, v[32:33] offset:2048
	flat_load_dword v55, v[34:35]
	flat_load_dword v56, v[34:35] offset:2048
	flat_load_dword v53, v[36:37]
	flat_load_dword v54, v[36:37] offset:2048
	v_add_co_u32_e32 v32, vcc, s0, v30
	s_movk_i32 s0, 0x5000
	s_nop 0
	v_addc_co_u32_e32 v33, vcc, 0, v31, vcc
	v_add_co_u32_e32 v34, vcc, s0, v30
	s_movk_i32 s0, 0x6000
	s_nop 0
	v_addc_co_u32_e32 v35, vcc, 0, v31, vcc
	v_add_co_u32_e32 v36, vcc, s0, v30
	s_movk_i32 s0, 0x7000
	s_nop 0
	v_addc_co_u32_e32 v37, vcc, 0, v31, vcc
	v_add_co_u32_e32 v38, vcc, s0, v30
	s_mov_b32 s0, 0x8000
	s_nop 0
	v_addc_co_u32_e32 v39, vcc, 0, v31, vcc
	flat_load_dword v51, v[32:33]
	flat_load_dword v52, v[32:33] offset:2048
	flat_load_dword v49, v[34:35]
	flat_load_dword v50, v[34:35] offset:2048
	flat_load_dword v47, v[36:37]
	flat_load_dword v48, v[36:37] offset:2048
	flat_load_dword v45, v[38:39]
	flat_load_dword v46, v[38:39] offset:2048
	v_add_co_u32_e32 v32, vcc, s0, v30
	s_mov_b32 s0, 0xc000
	s_nop 0
	v_addc_co_u32_e32 v33, vcc, 0, v31, vcc
	v_add_co_u32_e32 v34, vcc, 0x9000, v30
	v_add_u32_e32 v28, 0, v61
	s_nop 0
	v_addc_co_u32_e32 v35, vcc, 0, v31, vcc
	v_add_co_u32_e32 v36, vcc, s54, v30
	s_nop 1
	v_addc_co_u32_e32 v37, vcc, 0, v31, vcc
	v_add_co_u32_e32 v62, vcc, 0xb000, v30
	s_nop 1
	v_addc_co_u32_e32 v63, vcc, 0, v31, vcc
	flat_load_dword v43, v[32:33]
	flat_load_dword v44, v[32:33] offset:2048
	flat_load_dword v41, v[34:35]
	flat_load_dword v42, v[34:35] offset:2048
	flat_load_dword v39, v[36:37]
	flat_load_dword v40, v[36:37] offset:2048
	s_nop 0
	flat_load_dword v37, v[62:63]
	flat_load_dword v38, v[62:63] offset:2048
	v_add_co_u32_e32 v32, vcc, s0, v30
	s_nop 1
	v_addc_co_u32_e32 v33, vcc, 0, v31, vcc
	v_add_co_u32_e32 v62, vcc, 0xd000, v30
	s_nop 1
	v_addc_co_u32_e32 v63, vcc, 0, v31, vcc
	v_add_co_u32_e32 v64, vcc, 0xe000, v30
	s_nop 1
	v_addc_co_u32_e32 v65, vcc, 0, v31, vcc
	v_add_co_u32_e32 v66, vcc, 0xf000, v30
	s_nop 1
	v_addc_co_u32_e32 v67, vcc, 0, v31, vcc
	flat_load_dword v35, v[32:33]
	flat_load_dword v36, v[32:33] offset:2048
	s_nop 0
	flat_load_dword v33, v[62:63]
	flat_load_dword v34, v[62:63] offset:2048
	flat_load_dword v31, v[64:65]
	flat_load_dword v32, v[64:65] offset:2048
	flat_load_dword v25, v[66:67]
	flat_load_dword v30, v[66:67] offset:2048
	ds_read2_b32 v[62:63], v28 offset1:1
	v_add_lshl_u32 v28, s16, v2, 2
	s_waitcnt lgkmcnt(0)
	v_readfirstlane_b32 s6, v62
	v_readfirstlane_b32 s7, v63
	s_cmp_lg_u64 s[6:7], 0
	s_cselect_b64 s[24:25], -1, 0
	s_cmp_eq_u64 s[6:7], 0
	s_cbranch_scc1 .LBB0_1329
	v_lshlrev_b32_e32 v96, 2, v29
	v_lshl_add_u64 v[62:63], s[6:7], 0, v[96:97]
	global_load_dword v174, v[62:63], off
	global_load_dword v175, v[62:63], off offset:8
	global_load_dword v176, v[62:63], off offset:16
	global_load_dword v177, v[62:63], off offset:24
	global_load_dword v178, v[62:63], off offset:32
	global_load_dword v179, v[62:63], off offset:40
	global_load_dword v180, v[62:63], off offset:48
	global_load_dword v181, v[62:63], off offset:56
	global_load_dword v182, v[62:63], off offset:64
	global_load_dword v183, v[62:63], off offset:72
	global_load_dword v184, v[62:63], off offset:80
	global_load_dword v185, v[62:63], off offset:88
	global_load_dword v186, v[62:63], off offset:96
	global_load_dword v187, v[62:63], off offset:104
	global_load_dword v188, v[62:63], off offset:112
	global_load_dword v189, v[62:63], off offset:120
	global_load_dword v190, v[62:63], off offset:128
	global_load_dword v191, v[62:63], off offset:136
	global_load_dword v192, v[62:63], off offset:144
	global_load_dword v193, v[62:63], off offset:152
	global_load_dword v194, v[62:63], off offset:160
	global_load_dword v195, v[62:63], off offset:168
	global_load_dword v196, v[62:63], off offset:176
	global_load_dword v197, v[62:63], off offset:184
	global_load_dword v199, v[62:63], off offset:192
	global_load_dword v200, v[62:63], off offset:200
	global_load_dword v201, v[62:63], off offset:208
	global_load_dword v202, v[62:63], off offset:216
	global_load_dword v203, v[62:63], off offset:224
	global_load_dword v204, v[62:63], off offset:232
	global_load_dword v205, v[62:63], off offset:240
	global_load_dword v206, v[62:63], off offset:248
	s_nop 0
	s_waitcnt vmcnt(0) lgkmcnt(0)
	v_mul_f32_e32 v29, v59, v174
	ds_write_b32 v114, v29
	v_mov_b32_e32 v29, v97
	v_lshl_add_u64 v[62:63], s[6:7], 0, v[28:29]
	s_nop 0
	s_waitcnt vmcnt(0) lgkmcnt(0)
	v_mul_f32_e32 v29, v60, v175
	s_cbranch_execnz .LBB0_1059

.LBB0_1059:
	s_waitcnt vmcnt(0)
	v_add_u32_e32 v59, v1, v120
	ds_write_b32 v59, v29
	v_cndmask_b32_e64 v29, 0, 1, s[24:25]
	v_cmp_ne_u32_e64 s[0:1], 1, v29
	s_andn2_b64 vcc, exec, s[24:25]
	s_cbranch_vccnz .LBB0_1330
	v_mov_b32_e32 v29, v97
	v_lshl_add_u64 v[60:61], s[6:7], 0, v[28:29]
	s_nop 0
	v_add_u32_e32 v59, v1, v121
	s_waitcnt vmcnt(0) lgkmcnt(0)
	v_mul_f32_e32 v29, v57, v176
	ds_write_b32 v59, v29
	s_nop 0
	s_waitcnt vmcnt(0) lgkmcnt(0)
	v_mul_f32_e32 v29, v58, v177
	s_cbranch_execnz .LBB0_1062

.LBB0_1062:
	v_add_u32_e32 v57, v1, v122
	s_and_b64 vcc, exec, s[0:1]
	ds_write_b32 v57, v29
	s_cbranch_vccnz .LBB0_1331
	v_mov_b32_e32 v29, v97
	v_lshl_add_u64 v[58:59], s[6:7], 0, v[28:29]
	s_nop 0
	v_add_u32_e32 v57, v1, v123
	s_waitcnt vmcnt(0) lgkmcnt(0)
	v_mul_f32_e32 v29, v55, v178
	ds_write_b32 v57, v29
	s_nop 0
	s_waitcnt vmcnt(0) lgkmcnt(0)
	v_mul_f32_e32 v29, v56, v179
	s_cbranch_execnz .LBB0_1065

.LBB0_1065:
	v_add_u32_e32 v55, v1, v124
	s_and_b64 vcc, exec, s[0:1]
	ds_write_b32 v55, v29
	s_cbranch_vccnz .LBB0_1332
	v_mov_b32_e32 v29, v97
	v_lshl_add_u64 v[56:57], s[6:7], 0, v[28:29]
	s_nop 0
	v_add_u32_e32 v55, v1, v125
	s_waitcnt vmcnt(0) lgkmcnt(0)
	v_mul_f32_e32 v29, v53, v180
	ds_write_b32 v55, v29
	s_nop 0
	s_waitcnt vmcnt(0) lgkmcnt(0)
	v_mul_f32_e32 v29, v54, v181
	s_cbranch_execnz .LBB0_1068

.LBB0_1068:
	v_add_u32_e32 v53, v1, v126
	s_and_b64 vcc, exec, s[0:1]
	ds_write_b32 v53, v29
	s_cbranch_vccnz .LBB0_1333
	v_mov_b32_e32 v29, v97
	v_lshl_add_u64 v[54:55], s[6:7], 0, v[28:29]
	s_nop 0
	v_add_u32_e32 v53, v1, v127
	s_waitcnt vmcnt(0) lgkmcnt(0)
	v_mul_f32_e32 v29, v51, v182
	ds_write_b32 v53, v29
	s_nop 0
	s_waitcnt vmcnt(0) lgkmcnt(0)
	v_mul_f32_e32 v29, v52, v183
	s_cbranch_execnz .LBB0_1071

.LBB0_1071:
	v_add_u32_e32 v51, v1, v128
	s_and_b64 vcc, exec, s[0:1]
	ds_write_b32 v51, v29
	s_cbranch_vccnz .LBB0_1334
	v_mov_b32_e32 v29, v97
	v_lshl_add_u64 v[52:53], s[6:7], 0, v[28:29]
	s_nop 0
	v_add_u32_e32 v51, v1, v129
	s_waitcnt vmcnt(0) lgkmcnt(0)
	v_mul_f32_e32 v29, v49, v184
	ds_write_b32 v51, v29
	s_nop 0
	s_waitcnt vmcnt(0) lgkmcnt(0)
	v_mul_f32_e32 v29, v50, v185
	s_cbranch_execnz .LBB0_1074

.LBB0_1074:
	v_add_u32_e32 v49, v1, v130
	s_and_b64 vcc, exec, s[0:1]
	ds_write_b32 v49, v29
	s_cbranch_vccnz .LBB0_1335
	v_mov_b32_e32 v29, v97
	v_lshl_add_u64 v[50:51], s[6:7], 0, v[28:29]
	s_nop 0
	v_add_u32_e32 v49, v1, v131
	s_waitcnt vmcnt(0) lgkmcnt(0)
	v_mul_f32_e32 v29, v47, v186
	ds_write_b32 v49, v29
	s_nop 0
	s_waitcnt vmcnt(0) lgkmcnt(0)
	v_mul_f32_e32 v29, v48, v187
	s_cbranch_execnz .LBB0_1077

.LBB0_1077:
	v_add_u32_e32 v47, v1, v132
	s_and_b64 vcc, exec, s[0:1]
	ds_write_b32 v47, v29
	s_cbranch_vccnz .LBB0_1336
	v_mov_b32_e32 v29, v97
	v_lshl_add_u64 v[48:49], s[6:7], 0, v[28:29]
	s_nop 0
	v_add_u32_e32 v47, v1, v133
	s_waitcnt vmcnt(0) lgkmcnt(0)
	v_mul_f32_e32 v29, v45, v188
	ds_write_b32 v47, v29
	s_nop 0
	s_waitcnt vmcnt(0) lgkmcnt(0)
	v_mul_f32_e32 v29, v46, v189
	s_cbranch_execnz .LBB0_1080

.LBB0_1080:
	v_add_u32_e32 v45, v1, v134
	s_and_b64 vcc, exec, s[0:1]
	ds_write_b32 v45, v29
	s_cbranch_vccnz .LBB0_1337
	v_mov_b32_e32 v29, v97
	v_lshl_add_u64 v[46:47], s[6:7], 0, v[28:29]
	s_nop 0
	v_add_u32_e32 v45, v1, v135
	s_waitcnt vmcnt(0) lgkmcnt(0)
	v_mul_f32_e32 v29, v43, v190
	ds_write_b32 v45, v29
	s_nop 0
	s_waitcnt vmcnt(0) lgkmcnt(0)
	v_mul_f32_e32 v29, v44, v191
	s_cbranch_execnz .LBB0_1083

.LBB0_1083:
	v_add_u32_e32 v43, v1, v136
	s_and_b64 vcc, exec, s[0:1]
	ds_write_b32 v43, v29
	s_cbranch_vccnz .LBB0_1338
	v_mov_b32_e32 v29, v97
	v_lshl_add_u64 v[44:45], s[6:7], 0, v[28:29]
	s_nop 0
	v_add_u32_e32 v43, v1, v137
	s_waitcnt vmcnt(0) lgkmcnt(0)
	v_mul_f32_e32 v29, v41, v192
	ds_write_b32 v43, v29
	s_nop 0
	s_waitcnt vmcnt(0) lgkmcnt(0)
	v_mul_f32_e32 v29, v42, v193
	s_cbranch_execnz .LBB0_1086

.LBB0_1086:
	v_add_u32_e32 v41, v1, v138
	s_and_b64 vcc, exec, s[0:1]
	ds_write_b32 v41, v29
	s_cbranch_vccnz .LBB0_1339
	v_mov_b32_e32 v29, v97
	v_lshl_add_u64 v[42:43], s[6:7], 0, v[28:29]
	s_nop 0
	v_add_u32_e32 v41, v1, v139
	s_waitcnt vmcnt(0) lgkmcnt(0)
	v_mul_f32_e32 v29, v39, v194
	ds_write_b32 v41, v29
	s_nop 0
	s_waitcnt vmcnt(0) lgkmcnt(0)
	v_mul_f32_e32 v29, v40, v195
	s_cbranch_execnz .LBB0_1089

.LBB0_1089:
	v_add_u32_e32 v39, v1, v140
	s_and_b64 vcc, exec, s[0:1]
	ds_write_b32 v39, v29
	s_cbranch_vccnz .LBB0_1340
	v_mov_b32_e32 v29, v97
	v_lshl_add_u64 v[40:41], s[6:7], 0, v[28:29]
	s_nop 0
	v_add_u32_e32 v39, v1, v141
	s_waitcnt vmcnt(0) lgkmcnt(0)
	v_mul_f32_e32 v29, v37, v196
	ds_write_b32 v39, v29
	s_nop 0
	s_waitcnt vmcnt(0) lgkmcnt(0)
	v_mul_f32_e32 v29, v38, v197
	s_cbranch_execnz .LBB0_1092

.LBB0_1092:
	v_add_u32_e32 v37, v1, v142
	s_and_b64 vcc, exec, s[0:1]
	ds_write_b32 v37, v29
	s_cbranch_vccnz .LBB0_1341
	v_mov_b32_e32 v29, v97
	v_lshl_add_u64 v[38:39], s[6:7], 0, v[28:29]
	s_nop 0
	v_add_u32_e32 v37, v1, v143
	s_waitcnt vmcnt(0) lgkmcnt(0)
	v_mul_f32_e32 v29, v35, v199
	ds_write_b32 v37, v29
	s_nop 0
	s_waitcnt vmcnt(0) lgkmcnt(0)
	v_mul_f32_e32 v29, v36, v200
	s_cbranch_execnz .LBB0_1095

.LBB0_1095:
	v_add_u32_e32 v35, v1, v144
	s_and_b64 vcc, exec, s[0:1]
	ds_write_b32 v35, v29
	s_cbranch_vccnz .LBB0_1342
	v_mov_b32_e32 v29, v97
	v_lshl_add_u64 v[36:37], s[6:7], 0, v[28:29]
	s_nop 0
	s_waitcnt vmcnt(0) lgkmcnt(0)
	v_mul_f32_e32 v29, v33, v201
	ds_write_b32 v35, v29 offset:264
	s_nop 0
	s_waitcnt vmcnt(0) lgkmcnt(0)
	v_mul_f32_e32 v29, v34, v202
	s_cbranch_execnz .LBB0_1098

.LBB0_1098:
	s_and_b64 vcc, exec, s[0:1]
	ds_write_b32 v35, v29 offset:528
	s_cbranch_vccnz .LBB0_1343
	v_mov_b32_e32 v29, v97
	v_lshl_add_u64 v[36:37], s[6:7], 0, v[28:29]
	s_nop 0
	s_waitcnt vmcnt(0) lgkmcnt(0)
	v_mul_f32_e32 v29, v31, v203
	ds_write_b32 v35, v29 offset:792
	s_nop 0
	s_waitcnt vmcnt(0) lgkmcnt(0)
	v_mul_f32_e32 v29, v32, v204
	s_cbranch_execnz .LBB0_1101

.LBB0_1101:
	s_and_b64 vcc, exec, s[0:1]
	ds_write_b32 v35, v29 offset:1056
	s_cbranch_vccnz .LBB0_1344
	v_mov_b32_e32 v29, v97
	v_lshl_add_u64 v[28:29], s[6:7], 0, v[28:29]
	s_nop 0
	s_waitcnt vmcnt(0) lgkmcnt(0)
	v_mul_f32_e32 v31, v25, v205
	ds_write_b32 v35, v31 offset:1320
	s_nop 0
	s_waitcnt vmcnt(0) lgkmcnt(0)
	v_mul_f32_e32 v28, v30, v206
	s_cbranch_execnz .LBB0_1104

.LBB0_1131:
	s_lshl_b32 s16, s1, 6
	s_ashr_i32 s1, s0, 31
	s_lshl_b64 s[0:1], s[0:1], 2
	s_add_u32 s0, s2, s0
	v_or_b32_e32 v61, s16, v2
	s_addc_u32 s1, s14, s1
	v_lshlrev_b32_e32 v96, 2, v0
	v_lshl_add_u64 v[28:29], s[0:1], 0, v[96:97]
	s_movk_i32 s0, 0x5400
	v_mul_u32_u24_e32 v96, 0x1500, v61
	v_mad_u64_u32 v[30:31], s[0:1], v61, s0, v[28:29]
	v_lshl_add_u64 v[28:29], v[96:97], 2, v[28:29]
	flat_load_dword v59, v[30:31]
	v_add_co_u32_e32 v30, vcc, s54, v28
	s_mov_b32 s0, 0x15000
	s_nop 0
	v_addc_co_u32_e32 v31, vcc, 0, v29, vcc
	flat_load_dword v60, v[30:31] offset:2048
	v_add_co_u32_e32 v30, vcc, s0, v28
	s_mov_b32 s0, 0x1f000
	s_nop 0
	v_addc_co_u32_e32 v31, vcc, 0, v29, vcc
	flat_load_dword v57, v[30:31]
	v_add_co_u32_e32 v30, vcc, s0, v28
	s_mov_b32 s0, 0x34000
	s_nop 0
	v_addc_co_u32_e32 v31, vcc, 0, v29, vcc
	flat_load_dword v58, v[30:31] offset:2048
	v_add_co_u32_e32 v30, vcc, s56, v28
	s_cmp_lg_u64 s[6:7], 0
	s_nop 0
	v_addc_co_u32_e32 v31, vcc, 0, v29, vcc
	flat_load_dword v54, v[30:31]
	v_add_co_u32_e32 v30, vcc, s0, v28
	s_mov_b32 s0, 0x3f000
	s_nop 0
	v_addc_co_u32_e32 v31, vcc, 0, v29, vcc
	flat_load_dword v56, v[30:31] offset:2048
	v_add_co_u32_e32 v30, vcc, s0, v28
	s_mov_b32 s0, 0x49000
	s_nop 0
	v_addc_co_u32_e32 v31, vcc, 0, v29, vcc
	flat_load_dword v53, v[30:31]
	v_add_co_u32_e32 v30, vcc, s0, v28
	s_mov_b32 s0, 0x54000
	s_nop 0
	v_addc_co_u32_e32 v31, vcc, 0, v29, vcc
	flat_load_dword v55, v[30:31] offset:2048
	v_add_co_u32_e32 v30, vcc, s0, v28
	s_mov_b32 s0, 0x5e000
	s_nop 0
	v_addc_co_u32_e32 v31, vcc, 0, v29, vcc
	flat_load_dword v51, v[30:31]
	v_add_co_u32_e32 v30, vcc, s0, v28
	s_mov_b32 s0, 0x69000
	s_nop 0
	v_addc_co_u32_e32 v31, vcc, 0, v29, vcc
	flat_load_dword v52, v[30:31] offset:2048
	v_add_co_u32_e32 v30, vcc, s0, v28
	s_mov_b32 s0, 0x73000
	s_nop 0
	v_addc_co_u32_e32 v31, vcc, 0, v29, vcc
	flat_load_dword v49, v[30:31]
	v_add_co_u32_e32 v30, vcc, s0, v28
	s_mov_b32 s0, 0x7e000
	s_nop 0
	v_addc_co_u32_e32 v31, vcc, 0, v29, vcc
	flat_load_dword v50, v[30:31] offset:2048
	v_add_co_u32_e32 v30, vcc, s0, v28
	s_mov_b32 s0, 0x88000
	s_nop 0
	v_addc_co_u32_e32 v31, vcc, 0, v29, vcc
	flat_load_dword v46, v[30:31]
	v_add_co_u32_e32 v30, vcc, s0, v28
	s_mov_b32 s0, 0x93000
	s_nop 0
	v_addc_co_u32_e32 v31, vcc, 0, v29, vcc
	flat_load_dword v48, v[30:31] offset:2048
	v_add_co_u32_e32 v30, vcc, s0, v28
	s_mov_b32 s0, 0x9d000
	s_nop 0
	v_addc_co_u32_e32 v31, vcc, 0, v29, vcc
	flat_load_dword v45, v[30:31]
	v_add_co_u32_e32 v30, vcc, s0, v28
	s_mov_b32 s0, 0xa8000
	s_nop 0
	v_addc_co_u32_e32 v31, vcc, 0, v29, vcc
	flat_load_dword v47, v[30:31] offset:2048
	v_add_co_u32_e32 v30, vcc, s0, v28
	s_mov_b32 s0, 0xb2000
	s_nop 0
	v_addc_co_u32_e32 v31, vcc, 0, v29, vcc
	flat_load_dword v43, v[30:31]
	v_add_co_u32_e32 v30, vcc, s0, v28
	s_mov_b32 s0, 0xbd000
	s_nop 0
	v_addc_co_u32_e32 v31, vcc, 0, v29, vcc
	flat_load_dword v44, v[30:31] offset:2048
	v_add_co_u32_e32 v30, vcc, s0, v28
	s_mov_b32 s0, 0xc7000
	s_nop 0
	v_addc_co_u32_e32 v31, vcc, 0, v29, vcc
	flat_load_dword v41, v[30:31]
	v_add_co_u32_e32 v30, vcc, s0, v28
	s_mov_b32 s0, 0xd2000
	s_nop 0
	v_addc_co_u32_e32 v31, vcc, 0, v29, vcc
	flat_load_dword v42, v[30:31] offset:2048
	v_add_co_u32_e32 v30, vcc, s0, v28
	s_mov_b32 s0, 0xdc000
	s_nop 0
	v_addc_co_u32_e32 v31, vcc, 0, v29, vcc
	flat_load_dword v38, v[30:31]
	v_add_co_u32_e32 v30, vcc, s0, v28
	s_mov_b32 s0, 0xe7000
	s_nop 0
	v_addc_co_u32_e32 v31, vcc, 0, v29, vcc
	flat_load_dword v40, v[30:31] offset:2048
	v_add_co_u32_e32 v30, vcc, s0, v28
	s_mov_b32 s0, 0xf1000
	s_nop 0
	v_addc_co_u32_e32 v31, vcc, 0, v29, vcc
	flat_load_dword v37, v[30:31]
	v_add_co_u32_e32 v30, vcc, s0, v28
	s_mov_b32 s0, 0xfc000
	s_nop 0
	v_addc_co_u32_e32 v31, vcc, 0, v29, vcc
	flat_load_dword v39, v[30:31] offset:2048
	v_add_co_u32_e32 v30, vcc, s0, v28
	s_mov_b32 s0, 0x106000
	s_nop 0
	v_addc_co_u32_e32 v31, vcc, 0, v29, vcc
	flat_load_dword v35, v[30:31]
	v_add_co_u32_e32 v30, vcc, s0, v28
	s_mov_b32 s0, 0x111000
	s_nop 0
	v_addc_co_u32_e32 v31, vcc, 0, v29, vcc
	flat_load_dword v36, v[30:31] offset:2048
	v_add_co_u32_e32 v30, vcc, s0, v28
	s_mov_b32 s0, 0x11b000
	s_nop 0
	v_addc_co_u32_e32 v31, vcc, 0, v29, vcc
	flat_load_dword v33, v[30:31]
	v_add_co_u32_e32 v30, vcc, s0, v28
	s_mov_b32 s0, 0x126000
	s_nop 0
	v_addc_co_u32_e32 v31, vcc, 0, v29, vcc
	flat_load_dword v34, v[30:31] offset:2048
	v_add_co_u32_e32 v30, vcc, s0, v28
	s_cselect_b64 s[24:25], -1, 0
	s_nop 0
	v_addc_co_u32_e32 v31, vcc, 0, v29, vcc
	v_add_co_u32_e32 v62, vcc, 0x130000, v28
	flat_load_dword v30, v[30:31]
	s_nop 0
	v_addc_co_u32_e32 v63, vcc, 0, v29, vcc
	flat_load_dword v31, v[62:63] offset:2048
	v_add_co_u32_e32 v62, vcc, 0x13b000, v28
	s_cmp_eq_u64 s[6:7], 0
	s_nop 0
	v_addc_co_u32_e32 v63, vcc, 0, v29, vcc
	v_add_co_u32_e32 v28, vcc, 0x145000, v28
	flat_load_dword v25, v[62:63]
	s_nop 0
	v_addc_co_u32_e32 v29, vcc, 0, v29, vcc
	flat_load_dword v32, v[28:29] offset:2048
	v_add_lshl_u32 v28, s16, v2, 2
	s_cbranch_scc1 .LBB0_1313
	v_lshlrev_b32_e32 v96, 2, v61
	v_lshl_add_u64 v[62:63], s[6:7], 0, v[96:97]
	global_load_dword v174, v[62:63], off
	global_load_dword v175, v[62:63], off offset:8
	global_load_dword v176, v[62:63], off offset:16
	global_load_dword v177, v[62:63], off offset:24
	global_load_dword v178, v[62:63], off offset:32
	global_load_dword v179, v[62:63], off offset:40
	global_load_dword v180, v[62:63], off offset:48
	global_load_dword v181, v[62:63], off offset:56
	global_load_dword v182, v[62:63], off offset:64
	global_load_dword v183, v[62:63], off offset:72
	global_load_dword v184, v[62:63], off offset:80
	global_load_dword v185, v[62:63], off offset:88
	global_load_dword v186, v[62:63], off offset:96
	global_load_dword v187, v[62:63], off offset:104
	global_load_dword v188, v[62:63], off offset:112
	global_load_dword v189, v[62:63], off offset:120
	global_load_dword v190, v[62:63], off offset:128
	global_load_dword v191, v[62:63], off offset:136
	global_load_dword v192, v[62:63], off offset:144
	global_load_dword v193, v[62:63], off offset:152
	global_load_dword v194, v[62:63], off offset:160
	global_load_dword v195, v[62:63], off offset:168
	global_load_dword v196, v[62:63], off offset:176
	global_load_dword v197, v[62:63], off offset:184
	global_load_dword v199, v[62:63], off offset:192
	global_load_dword v200, v[62:63], off offset:200
	global_load_dword v201, v[62:63], off offset:208
	global_load_dword v202, v[62:63], off offset:216
	global_load_dword v203, v[62:63], off offset:224
	global_load_dword v204, v[62:63], off offset:232
	global_load_dword v205, v[62:63], off offset:240
	global_load_dword v206, v[62:63], off offset:248
	s_nop 0
	s_waitcnt vmcnt(0) lgkmcnt(0)
	v_mul_f32_e32 v29, v59, v174
	ds_write_b32 v114, v29
	v_mov_b32_e32 v29, v97
	v_lshl_add_u64 v[62:63], s[6:7], 0, v[28:29]
	s_nop 0
	s_waitcnt vmcnt(0) lgkmcnt(0)
	v_mul_f32_e32 v29, v60, v175
	s_cbranch_execnz .LBB0_1134

.LBB0_1134:
	s_waitcnt vmcnt(0) lgkmcnt(0)
	v_add_u32_e32 v59, v1, v120
	ds_write_b32 v59, v29
	v_cndmask_b32_e64 v29, 0, 1, s[24:25]
	v_cmp_ne_u32_e64 s[0:1], 1, v29
	s_andn2_b64 vcc, exec, s[24:25]
	s_cbranch_vccnz .LBB0_1314
	v_mov_b32_e32 v29, v97
	v_lshl_add_u64 v[60:61], s[6:7], 0, v[28:29]
	s_nop 0
	v_add_u32_e32 v59, v1, v121
	s_waitcnt vmcnt(0) lgkmcnt(0)
	v_mul_f32_e32 v29, v57, v176
	ds_write_b32 v59, v29
	s_nop 0
	s_waitcnt vmcnt(0) lgkmcnt(0)
	v_mul_f32_e32 v29, v58, v177
	s_cbranch_execnz .LBB0_1137

.LBB0_1137:
	v_add_u32_e32 v57, v1, v122
	s_and_b64 vcc, exec, s[0:1]
	ds_write_b32 v57, v29
	s_cbranch_vccnz .LBB0_1315
	v_mov_b32_e32 v29, v97
	v_lshl_add_u64 v[58:59], s[6:7], 0, v[28:29]
	s_nop 0
	v_add_u32_e32 v57, v1, v123
	s_waitcnt vmcnt(0) lgkmcnt(0)
	v_mul_f32_e32 v29, v54, v178
	ds_write_b32 v57, v29
	s_nop 0
	s_waitcnt vmcnt(0) lgkmcnt(0)
	v_mul_f32_e32 v29, v56, v179
	s_cbranch_execnz .LBB0_1140

.LBB0_1140:
	v_add_u32_e32 v54, v1, v124
	s_and_b64 vcc, exec, s[0:1]
	ds_write_b32 v54, v29
	s_cbranch_vccnz .LBB0_1316
	v_mov_b32_e32 v29, v97
	v_lshl_add_u64 v[56:57], s[6:7], 0, v[28:29]
	s_nop 0
	v_add_u32_e32 v54, v1, v125
	s_waitcnt vmcnt(0) lgkmcnt(0)
	v_mul_f32_e32 v29, v53, v180
	ds_write_b32 v54, v29
	s_nop 0
	s_waitcnt vmcnt(0) lgkmcnt(0)
	v_mul_f32_e32 v29, v55, v181
	s_cbranch_execnz .LBB0_1143

.LBB0_1149:
	v_add_u32_e32 v49, v1, v130
	s_and_b64 vcc, exec, s[0:1]
	ds_write_b32 v49, v29
	s_cbranch_vccnz .LBB0_1319
	v_mov_b32_e32 v29, v97
	v_lshl_add_u64 v[50:51], s[6:7], 0, v[28:29]
	s_nop 0
	v_add_u32_e32 v49, v1, v131
	s_waitcnt vmcnt(0) lgkmcnt(0)
	v_mul_f32_e32 v29, v46, v186
	ds_write_b32 v49, v29
	s_nop 0
	s_waitcnt vmcnt(0) lgkmcnt(0)
	v_mul_f32_e32 v29, v48, v187
	s_cbranch_execnz .LBB0_1152

.LBB0_1152:
	v_add_u32_e32 v46, v1, v132
	s_and_b64 vcc, exec, s[0:1]
	ds_write_b32 v46, v29
	s_cbranch_vccnz .LBB0_1320
	v_mov_b32_e32 v29, v97
	v_lshl_add_u64 v[48:49], s[6:7], 0, v[28:29]
	s_nop 0
	v_add_u32_e32 v46, v1, v133
	s_waitcnt vmcnt(0) lgkmcnt(0)
	v_mul_f32_e32 v29, v45, v188
	ds_write_b32 v46, v29
	s_nop 0
	s_waitcnt vmcnt(0) lgkmcnt(0)
	v_mul_f32_e32 v29, v47, v189
	s_cbranch_execnz .LBB0_1155

.LBB0_1161:
	v_add_u32_e32 v41, v1, v138
	s_and_b64 vcc, exec, s[0:1]
	ds_write_b32 v41, v29
	s_cbranch_vccnz .LBB0_1323
	v_mov_b32_e32 v29, v97
	v_lshl_add_u64 v[42:43], s[6:7], 0, v[28:29]
	s_nop 0
	v_add_u32_e32 v41, v1, v139
	s_waitcnt vmcnt(0) lgkmcnt(0)
	v_mul_f32_e32 v29, v38, v194
	ds_write_b32 v41, v29
	s_nop 0
	s_waitcnt vmcnt(0) lgkmcnt(0)
	v_mul_f32_e32 v29, v40, v195
	s_cbranch_execnz .LBB0_1164

.LBB0_1164:
	v_add_u32_e32 v38, v1, v140
	s_and_b64 vcc, exec, s[0:1]
	ds_write_b32 v38, v29
	s_cbranch_vccnz .LBB0_1324
	v_mov_b32_e32 v29, v97
	v_lshl_add_u64 v[40:41], s[6:7], 0, v[28:29]
	s_nop 0
	v_add_u32_e32 v38, v1, v141
	s_waitcnt vmcnt(0) lgkmcnt(0)
	v_mul_f32_e32 v29, v37, v196
	ds_write_b32 v38, v29
	s_nop 0
	s_waitcnt vmcnt(0) lgkmcnt(0)
	v_mul_f32_e32 v29, v39, v197
	s_cbranch_execnz .LBB0_1167

.LBB0_1173:
	s_and_b64 vcc, exec, s[0:1]
	ds_write_b32 v35, v29 offset:528
	s_cbranch_vccnz .LBB0_1327
	v_mov_b32_e32 v29, v97
	v_lshl_add_u64 v[36:37], s[6:7], 0, v[28:29]
	s_nop 0
	s_waitcnt vmcnt(0) lgkmcnt(0)
	v_mul_f32_e32 v29, v30, v203
	ds_write_b32 v35, v29 offset:792
	s_nop 0
	s_waitcnt vmcnt(0) lgkmcnt(0)
	v_mul_f32_e32 v29, v31, v204
	s_cbranch_execnz .LBB0_1176

.LBB0_1176:
	s_and_b64 vcc, exec, s[0:1]
	ds_write_b32 v35, v29 offset:1056
	s_cbranch_vccnz .LBB0_1328
	v_mov_b32_e32 v29, v97
	v_lshl_add_u64 v[28:29], s[6:7], 0, v[28:29]
	s_nop 0
	s_waitcnt vmcnt(0) lgkmcnt(0)
	v_mul_f32_e32 v30, v25, v205
	ds_write_b32 v35, v30 offset:1320
	s_nop 0
	s_waitcnt vmcnt(0) lgkmcnt(0)
	v_mul_f32_e32 v28, v32, v206
	s_cbranch_execnz .LBB0_1179

.LBB0_1181:
	s_andn2_b64 vcc, exec, s[0:1]
	s_cbranch_vccnz .LBB0_1231
	s_add_i32 s0, s46, 0xfffff500
	s_mul_i32 s1, s0, 0xba2f
	s_lshr_b32 s1, s1, 23
	s_mul_i32 s7, s1, 0xffffff50
	v_mov_b32_e32 v25, 0x204f0
	s_add_i32 s7, s7, s0
	s_lshl_b32 s15, s7, 5
	s_lshl_b32 s7, s7, 4
	v_add_u32_e32 v25, 0, v25
	s_and_b32 s0, s15, 0xe0
	s_and_b32 s7, s7, 0xffffff80
	ds_read2_b32 v[28:29], v25 offset1:1
	s_or_b32 s14, s7, s0
	s_add_i32 s7, s0, s7
	s_addk_i32 s7, 0xa80
	s_cmpk_lt_u32 s0, 0x80
	s_cselect_b32 s0, s14, s7
	s_lshl_b32 s16, s1, 6
	s_ashr_i32 s1, s0, 31
	s_waitcnt lgkmcnt(0)
	v_readfirstlane_b32 s2, v28
	s_lshl_b64 s[0:1], s[0:1], 2
	v_readfirstlane_b32 s6, v29
	s_add_u32 s0, s2, s0
	v_or_b32_e32 v29, s16, v2
	s_addc_u32 s1, s6, s1
	v_lshlrev_b32_e32 v96, 2, v0
	v_lshl_add_u64 v[30:31], s[0:1], 0, v[96:97]
	v_mul_u32_u24_e32 v96, 0x5800, v29
	v_mad_u64_u32 v[32:33], s[0:1], v29, s3, v[30:31]
	v_lshl_add_u64 v[30:31], v[30:31], 0, v[96:97]
	v_add_co_u32_e32 v34, vcc, s55, v30
	s_mov_b32 s0, 0x21000
	s_nop 0
	v_addc_co_u32_e32 v35, vcc, 0, v31, vcc
	v_add_co_u32_e32 v36, vcc, s35, v30
	v_mov_b32_e32 v61, 0x204e8
	s_nop 0
	v_addc_co_u32_e32 v37, vcc, 0, v31, vcc
	v_add_co_u32_e32 v38, vcc, s0, v30
	s_mov_b32 s0, 0x37000
	s_nop 0
	v_addc_co_u32_e32 v39, vcc, 0, v31, vcc
	v_add_co_u32_e32 v40, vcc, s57, v30
	s_nop 1
	v_addc_co_u32_e32 v41, vcc, 0, v31, vcc
	v_add_co_u32_e32 v42, vcc, s0, v30
	s_mov_b32 s0, 0x42000
	s_nop 0
	v_addc_co_u32_e32 v43, vcc, 0, v31, vcc
	v_add_co_u32_e32 v44, vcc, s0, v30
	s_mov_b32 s0, 0x4d000
	s_nop 0
	v_addc_co_u32_e32 v45, vcc, 0, v31, vcc
	v_add_co_u32_e32 v46, vcc, s0, v30
	s_mov_b32 s0, 0x58000
	s_nop 0
	v_addc_co_u32_e32 v47, vcc, 0, v31, vcc
	flat_load_dword v59, v[32:33]
	flat_load_dword v60, v[34:35]
	flat_load_dword v57, v[36:37]
	flat_load_dword v58, v[38:39]
	flat_load_dword v55, v[40:41]
	flat_load_dword v56, v[42:43]
	flat_load_dword v51, v[44:45]
	flat_load_dword v52, v[46:47]
	v_add_co_u32_e32 v32, vcc, s0, v30
	s_mov_b32 s0, 0x63000
	s_nop 0
	v_addc_co_u32_e32 v33, vcc, 0, v31, vcc
	v_add_co_u32_e32 v34, vcc, s0, v30
	s_mov_b32 s0, 0x6e000
	s_nop 0
	v_addc_co_u32_e32 v35, vcc, 0, v31, vcc
	v_add_co_u32_e32 v36, vcc, s0, v30
	s_mov_b32 s0, 0x79000
	s_nop 0
	v_addc_co_u32_e32 v37, vcc, 0, v31, vcc
	v_add_co_u32_e32 v38, vcc, s0, v30
	s_mov_b32 s0, 0x84000
	s_nop 0
	v_addc_co_u32_e32 v39, vcc, 0, v31, vcc
	v_add_co_u32_e32 v40, vcc, s0, v30
	s_mov_b32 s0, 0x8f000
	s_nop 0
	v_addc_co_u32_e32 v41, vcc, 0, v31, vcc
	v_add_co_u32_e32 v42, vcc, s0, v30
	s_mov_b32 s0, 0x9a000
	s_nop 0
	v_addc_co_u32_e32 v43, vcc, 0, v31, vcc
	v_add_co_u32_e32 v44, vcc, s0, v30
	s_mov_b32 s0, 0xa5000
	s_nop 0
	v_addc_co_u32_e32 v45, vcc, 0, v31, vcc
	v_add_co_u32_e32 v62, vcc, s0, v30
	s_mov_b32 s0, 0xb0000
	s_nop 0
	v_addc_co_u32_e32 v63, vcc, 0, v31, vcc
	flat_load_dword v53, v[32:33]
	flat_load_dword v54, v[34:35]
	flat_load_dword v49, v[36:37]
	flat_load_dword v50, v[38:39]
	flat_load_dword v47, v[40:41]
	flat_load_dword v48, v[42:43]
	s_nop 0
	flat_load_dword v43, v[44:45]
	s_nop 0
	flat_load_dword v44, v[62:63]
	v_add_co_u32_e32 v32, vcc, s0, v30
	s_mov_b32 s0, 0xbb000
	s_nop 0
	v_addc_co_u32_e32 v33, vcc, 0, v31, vcc
	v_add_co_u32_e32 v34, vcc, s0, v30
	s_mov_b32 s0, 0xc6000
	s_nop 0
	v_addc_co_u32_e32 v35, vcc, 0, v31, vcc
	v_add_co_u32_e32 v36, vcc, s0, v30
	s_mov_b32 s0, 0xd1000
	s_nop 0
	v_addc_co_u32_e32 v37, vcc, 0, v31, vcc
	v_add_co_u32_e32 v38, vcc, s0, v30
	s_mov_b32 s0, 0xdc000
	s_nop 0
	v_addc_co_u32_e32 v39, vcc, 0, v31, vcc
	v_add_co_u32_e32 v62, vcc, s0, v30
	s_mov_b32 s0, 0xe7000
	s_nop 0
	v_addc_co_u32_e32 v63, vcc, 0, v31, vcc
	v_add_co_u32_e32 v64, vcc, s0, v30
	s_mov_b32 s0, 0xf2000
	s_nop 0
	v_addc_co_u32_e32 v65, vcc, 0, v31, vcc
	v_add_co_u32_e32 v66, vcc, s0, v30
	s_mov_b32 s0, 0xfd000
	s_nop 0
	v_addc_co_u32_e32 v67, vcc, 0, v31, vcc
	v_add_co_u32_e32 v68, vcc, s0, v30
	s_mov_b32 s0, 0x108000
	s_nop 0
	v_addc_co_u32_e32 v69, vcc, 0, v31, vcc
	flat_load_dword v45, v[32:33]
	flat_load_dword v46, v[34:35]
	flat_load_dword v41, v[36:37]
	flat_load_dword v42, v[38:39]
	s_nop 0
	flat_load_dword v39, v[62:63]
	flat_load_dword v40, v[64:65]
	flat_load_dword v35, v[66:67]
	flat_load_dword v36, v[68:69]
	v_add_co_u32_e32 v32, vcc, s0, v30
	s_mov_b32 s0, 0x113000
	s_nop 0
	v_addc_co_u32_e32 v33, vcc, 0, v31, vcc
	v_add_co_u32_e32 v62, vcc, s0, v30
	s_mov_b32 s0, 0x11e000
	s_nop 0
	v_addc_co_u32_e32 v63, vcc, 0, v31, vcc
	v_add_co_u32_e32 v64, vcc, s0, v30
	s_mov_b32 s0, 0x129000
	s_nop 0
	v_addc_co_u32_e32 v65, vcc, 0, v31, vcc
	v_add_co_u32_e32 v66, vcc, s0, v30
	s_mov_b32 s0, 0x134000
	s_nop 0
	v_addc_co_u32_e32 v67, vcc, 0, v31, vcc
	v_add_co_u32_e32 v68, vcc, s0, v30
	v_add_u32_e32 v28, 0, v61
	s_nop 0
	v_addc_co_u32_e32 v69, vcc, 0, v31, vcc
	v_add_co_u32_e32 v70, vcc, 0x13f000, v30
	s_nop 1
	v_addc_co_u32_e32 v71, vcc, 0, v31, vcc
	v_add_co_u32_e32 v72, vcc, 0x14a000, v30
	s_nop 1
	v_addc_co_u32_e32 v73, vcc, 0, v31, vcc
	v_add_co_u32_e32 v74, vcc, 0x155000, v30
	s_nop 1
	v_addc_co_u32_e32 v75, vcc, 0, v31, vcc
	flat_load_dword v37, v[32:33]
	flat_load_dword v38, v[62:63]
	s_nop 0
	flat_load_dword v33, v[64:65]
	flat_load_dword v34, v[66:67]
	flat_load_dword v31, v[68:69]
	flat_load_dword v32, v[70:71]
	flat_load_dword v25, v[72:73]
	flat_load_dword v30, v[74:75]
	ds_read2_b32 v[62:63], v28 offset1:1
	v_add_lshl_u32 v28, s16, v2, 2
	s_waitcnt lgkmcnt(0)
	v_readfirstlane_b32 s6, v62
	v_readfirstlane_b32 s7, v63
	s_cmp_lg_u64 s[6:7], 0
	s_cselect_b64 s[24:25], -1, 0
	s_cmp_eq_u64 s[6:7], 0
	s_cbranch_scc1 .LBB0_1297
	v_lshlrev_b32_e32 v96, 2, v29
	v_lshl_add_u64 v[62:63], s[6:7], 0, v[96:97]
	global_load_dword v174, v[62:63], off
	global_load_dword v175, v[62:63], off offset:8
	global_load_dword v176, v[62:63], off offset:16
	global_load_dword v177, v[62:63], off offset:24
	global_load_dword v178, v[62:63], off offset:32
	global_load_dword v179, v[62:63], off offset:40
	global_load_dword v180, v[62:63], off offset:48
	global_load_dword v181, v[62:63], off offset:56
	global_load_dword v182, v[62:63], off offset:64
	global_load_dword v183, v[62:63], off offset:72
	global_load_dword v184, v[62:63], off offset:80
	global_load_dword v185, v[62:63], off offset:88
	global_load_dword v186, v[62:63], off offset:96
	global_load_dword v187, v[62:63], off offset:104
	global_load_dword v188, v[62:63], off offset:112
	global_load_dword v189, v[62:63], off offset:120
	global_load_dword v190, v[62:63], off offset:128
	global_load_dword v191, v[62:63], off offset:136
	global_load_dword v192, v[62:63], off offset:144
	global_load_dword v193, v[62:63], off offset:152
	global_load_dword v194, v[62:63], off offset:160
	global_load_dword v195, v[62:63], off offset:168
	global_load_dword v196, v[62:63], off offset:176
	global_load_dword v197, v[62:63], off offset:184
	global_load_dword v199, v[62:63], off offset:192
	global_load_dword v200, v[62:63], off offset:200
	global_load_dword v201, v[62:63], off offset:208
	global_load_dword v202, v[62:63], off offset:216
	global_load_dword v203, v[62:63], off offset:224
	global_load_dword v204, v[62:63], off offset:232
	global_load_dword v205, v[62:63], off offset:240
	global_load_dword v206, v[62:63], off offset:248
	s_nop 0
	s_waitcnt vmcnt(0) lgkmcnt(0)
	v_mul_f32_e32 v29, v59, v174
	ds_write_b32 v114, v29
	v_mov_b32_e32 v29, v97
	v_lshl_add_u64 v[62:63], s[6:7], 0, v[28:29]
	s_nop 0
	s_waitcnt vmcnt(0) lgkmcnt(0)
	v_mul_f32_e32 v29, v60, v175
	s_cbranch_execnz .LBB0_1185

.LBB0_1191:
	v_add_u32_e32 v55, v1, v124
	s_and_b64 vcc, exec, s[0:1]
	ds_write_b32 v55, v29
	s_cbranch_vccnz .LBB0_1300
	v_mov_b32_e32 v29, v97
	v_lshl_add_u64 v[56:57], s[6:7], 0, v[28:29]
	s_nop 0
	v_add_u32_e32 v55, v1, v125
	s_waitcnt vmcnt(0) lgkmcnt(0)
	v_mul_f32_e32 v29, v51, v180
	ds_write_b32 v55, v29
	s_nop 0
	s_waitcnt vmcnt(0) lgkmcnt(0)
	v_mul_f32_e32 v29, v52, v181
	s_cbranch_execnz .LBB0_1194

.LBB0_1194:
	v_add_u32_e32 v51, v1, v126
	s_and_b64 vcc, exec, s[0:1]
	ds_write_b32 v51, v29
	s_cbranch_vccnz .LBB0_1301
	v_mov_b32_e32 v29, v97
	v_lshl_add_u64 v[56:57], s[6:7], 0, v[28:29]
	s_nop 0
	v_add_u32_e32 v51, v1, v127
	s_waitcnt vmcnt(0) lgkmcnt(0)
	v_mul_f32_e32 v29, v53, v182
	ds_write_b32 v51, v29
	s_nop 0
	s_waitcnt vmcnt(0) lgkmcnt(0)
	v_mul_f32_e32 v29, v54, v183
	s_cbranch_execnz .LBB0_1197

.LBB0_1203:
	v_add_u32_e32 v47, v1, v132
	s_and_b64 vcc, exec, s[0:1]
	ds_write_b32 v47, v29
	s_cbranch_vccnz .LBB0_1304
	v_mov_b32_e32 v29, v97
	v_lshl_add_u64 v[48:49], s[6:7], 0, v[28:29]
	s_nop 0
	v_add_u32_e32 v47, v1, v133
	s_waitcnt vmcnt(0) lgkmcnt(0)
	v_mul_f32_e32 v29, v43, v188
	ds_write_b32 v47, v29
	s_nop 0
	s_waitcnt vmcnt(0) lgkmcnt(0)
	v_mul_f32_e32 v29, v44, v189
	s_cbranch_execnz .LBB0_1206

.LBB0_1206:
	v_add_u32_e32 v43, v1, v134
	s_and_b64 vcc, exec, s[0:1]
	ds_write_b32 v43, v29
	s_cbranch_vccnz .LBB0_1305
	v_mov_b32_e32 v29, v97
	v_lshl_add_u64 v[48:49], s[6:7], 0, v[28:29]
	s_nop 0
	v_add_u32_e32 v43, v1, v135
	s_waitcnt vmcnt(0) lgkmcnt(0)
	v_mul_f32_e32 v29, v45, v190
	ds_write_b32 v43, v29
	s_nop 0
	s_waitcnt vmcnt(0) lgkmcnt(0)
	v_mul_f32_e32 v29, v46, v191
	s_cbranch_execnz .LBB0_1209

.LBB0_1215:
	v_add_u32_e32 v39, v1, v140
	s_and_b64 vcc, exec, s[0:1]
	ds_write_b32 v39, v29
	s_cbranch_vccnz .LBB0_1308
	v_mov_b32_e32 v29, v97
	v_lshl_add_u64 v[40:41], s[6:7], 0, v[28:29]
	s_nop 0
	v_add_u32_e32 v39, v1, v141
	s_waitcnt vmcnt(0) lgkmcnt(0)
	v_mul_f32_e32 v29, v35, v196
	ds_write_b32 v39, v29
	s_nop 0
	s_waitcnt vmcnt(0) lgkmcnt(0)
	v_mul_f32_e32 v29, v36, v197
	s_cbranch_execnz .LBB0_1218

.LBB0_1218:
	v_add_u32_e32 v35, v1, v142
	s_and_b64 vcc, exec, s[0:1]
	ds_write_b32 v35, v29
	s_cbranch_vccnz .LBB0_1309
	v_mov_b32_e32 v29, v97
	v_lshl_add_u64 v[40:41], s[6:7], 0, v[28:29]
	s_nop 0
	v_add_u32_e32 v35, v1, v143
	s_waitcnt vmcnt(0) lgkmcnt(0)
	v_mul_f32_e32 v29, v37, v199
	ds_write_b32 v35, v29
	s_nop 0
	s_waitcnt vmcnt(0) lgkmcnt(0)
	v_mul_f32_e32 v29, v38, v200
	s_cbranch_execnz .LBB0_1221

.LBB0_1232:
	s_andn2_b64 vcc, exec, s[0:1]
	s_cbranch_vccnz .LBB0_1038
	s_mul_hi_i32 s0, s46, 0x2e8ba2e9
	s_lshr_b32 s1, s0, 31
	s_ashr_i32 s0, s0, 5
	s_add_i32 s1, s0, s1
	s_mul_i32 s0, s1, 0xffffff50
	v_mov_b32_e32 v25, 0x20418
	s_add_i32 s0, s0, s46
	s_lshl_b32 s15, s0, 5
	s_lshl_b32 s0, s0, 4
	v_add_u32_e32 v25, 0, v25
	s_and_b32 s6, s15, 0xe0
	s_and_b32 s0, s0, 0xffffff80
	ds_read2_b32 v[28:29], v25 offset1:1
	s_or_b32 s14, s0, s6
	s_add_i32 s0, s6, s0
	s_addk_i32 s0, 0xa80
	s_cmpk_lt_u32 s6, 0x80
	s_cselect_b32 s0, s14, s0
	s_lshl_b32 s6, s1, 6
	s_ashr_i32 s1, s0, 31
	s_waitcnt lgkmcnt(0)
	v_readfirstlane_b32 s2, v28
	s_lshl_b64 s[0:1], s[0:1], 2
	v_readfirstlane_b32 s7, v29
	s_add_u32 s0, s2, s0
	v_or_b32_e32 v28, s6, v2
	s_addc_u32 s1, s7, s1
	v_lshlrev_b32_e32 v96, 2, v0
	v_lshl_add_u64 v[30:31], s[0:1], 0, v[96:97]
	v_or_b32_e32 v25, 2, v28
	v_mad_i64_i32 v[34:35], s[0:1], v25, s3, v[30:31]
	v_or_b32_e32 v25, 4, v28
	v_mad_i64_i32 v[36:37], s[0:1], v25, s3, v[30:31]
	v_or_b32_e32 v25, 6, v28
	v_mad_i64_i32 v[38:39], s[0:1], v25, s3, v[30:31]
	v_or_b32_e32 v25, 8, v28
	v_mad_i64_i32 v[40:41], s[0:1], v25, s3, v[30:31]
	v_or_b32_e32 v25, 10, v28
	v_mad_i64_i32 v[42:43], s[0:1], v25, s3, v[30:31]
	v_or_b32_e32 v25, 12, v28
	v_mad_i64_i32 v[44:45], s[0:1], v25, s3, v[30:31]
	v_or_b32_e32 v25, 14, v28
	v_mov_b32_e32 v61, 0x20410
	v_mad_i64_i32 v[32:33], s[0:1], v28, s3, v[30:31]
	v_mad_i64_i32 v[46:47], s[0:1], v25, s3, v[30:31]
	v_or_b32_e32 v25, 16, v28
	flat_load_dword v59, v[32:33]
	flat_load_dword v60, v[34:35]
	flat_load_dword v57, v[36:37]
	flat_load_dword v58, v[38:39]
	flat_load_dword v55, v[40:41]
	flat_load_dword v56, v[42:43]
	flat_load_dword v53, v[44:45]
	flat_load_dword v54, v[46:47]
	v_mad_i64_i32 v[32:33], s[0:1], v25, s3, v[30:31]
	v_or_b32_e32 v25, 18, v28
	v_mad_i64_i32 v[34:35], s[0:1], v25, s3, v[30:31]
	v_or_b32_e32 v25, 20, v28
	v_mad_i64_i32 v[36:37], s[0:1], v25, s3, v[30:31]
	v_or_b32_e32 v25, 22, v28
	v_mad_i64_i32 v[38:39], s[0:1], v25, s3, v[30:31]
	v_or_b32_e32 v25, 24, v28
	v_mad_i64_i32 v[40:41], s[0:1], v25, s3, v[30:31]
	v_or_b32_e32 v25, 26, v28
	v_mad_i64_i32 v[42:43], s[0:1], v25, s3, v[30:31]
	v_or_b32_e32 v25, 28, v28
	v_mad_i64_i32 v[44:45], s[0:1], v25, s3, v[30:31]
	v_or_b32_e32 v25, 30, v28
	v_mad_i64_i32 v[62:63], s[0:1], v25, s3, v[30:31]
	v_or_b32_e32 v25, 32, v28
	flat_load_dword v51, v[32:33]
	flat_load_dword v52, v[34:35]
	flat_load_dword v49, v[36:37]
	flat_load_dword v50, v[38:39]
	flat_load_dword v47, v[40:41]
	flat_load_dword v48, v[42:43]
	s_nop 0
	flat_load_dword v45, v[44:45]
	s_nop 0
	flat_load_dword v46, v[62:63]
	v_mad_i64_i32 v[32:33], s[0:1], v25, s3, v[30:31]
	v_or_b32_e32 v25, 34, v28
	v_mad_i64_i32 v[34:35], s[0:1], v25, s3, v[30:31]
	v_or_b32_e32 v25, 36, v28
	v_mad_i64_i32 v[36:37], s[0:1], v25, s3, v[30:31]
	v_or_b32_e32 v25, 38, v28
	v_mad_i64_i32 v[38:39], s[0:1], v25, s3, v[30:31]
	v_or_b32_e32 v25, 40, v28
	v_mad_i64_i32 v[62:63], s[0:1], v25, s3, v[30:31]
	v_or_b32_e32 v25, 42, v28
	v_mad_i64_i32 v[64:65], s[0:1], v25, s3, v[30:31]
	v_or_b32_e32 v25, 44, v28
	v_mad_i64_i32 v[66:67], s[0:1], v25, s3, v[30:31]
	v_or_b32_e32 v25, 46, v28
	v_mad_i64_i32 v[68:69], s[0:1], v25, s3, v[30:31]
	v_or_b32_e32 v25, 48, v28
	flat_load_dword v43, v[32:33]
	flat_load_dword v44, v[34:35]
	flat_load_dword v41, v[36:37]
	flat_load_dword v42, v[38:39]
	s_nop 0
	flat_load_dword v39, v[62:63]
	flat_load_dword v40, v[64:65]
	flat_load_dword v37, v[66:67]
	flat_load_dword v38, v[68:69]
	v_mad_i64_i32 v[32:33], s[0:1], v25, s3, v[30:31]
	v_or_b32_e32 v25, 50, v28
	v_mad_i64_i32 v[62:63], s[0:1], v25, s3, v[30:31]
	v_or_b32_e32 v25, 52, v28
	v_mad_i64_i32 v[64:65], s[0:1], v25, s3, v[30:31]
	v_or_b32_e32 v25, 54, v28
	v_mad_i64_i32 v[66:67], s[0:1], v25, s3, v[30:31]
	v_or_b32_e32 v25, 56, v28
	v_mad_i64_i32 v[68:69], s[0:1], v25, s3, v[30:31]
	v_or_b32_e32 v25, 58, v28
	v_mad_i64_i32 v[70:71], s[0:1], v25, s3, v[30:31]
	v_or_b32_e32 v25, 60, v28
	v_mad_i64_i32 v[72:73], s[0:1], v25, s3, v[30:31]
	v_or_b32_e32 v25, 62, v28
	v_mad_i64_i32 v[74:75], s[0:1], v25, s3, v[30:31]
	flat_load_dword v35, v[32:33]
	flat_load_dword v36, v[62:63]
	s_nop 0
	flat_load_dword v33, v[64:65]
	flat_load_dword v34, v[66:67]
	flat_load_dword v31, v[68:69]
	flat_load_dword v32, v[70:71]
	flat_load_dword v30, v[72:73]
	flat_load_dword v25, v[74:75]
	v_add_u32_e32 v29, 0, v61
	ds_read2_b32 v[62:63], v29 offset1:1
	s_waitcnt lgkmcnt(0)
	v_readfirstlane_b32 s48, v62
	v_readfirstlane_b32 s49, v63
	s_cmp_lg_u64 s[48:49], 0
	s_cselect_b64 s[24:25], -1, 0
	s_cmp_eq_u64 s[48:49], 0
	s_cbranch_scc1 .LBB0_1280
	v_ashrrev_i32_e32 v29, 31, v28
	v_lshl_add_u64 v[28:29], v[28:29], 2, s[48:49]
	global_load_dword v174, v[28:29], off
	global_load_dword v175, v[28:29], off offset:8
	global_load_dword v176, v[28:29], off offset:16
	global_load_dword v177, v[28:29], off offset:24
	global_load_dword v178, v[28:29], off offset:32
	global_load_dword v179, v[28:29], off offset:40
	global_load_dword v180, v[28:29], off offset:48
	global_load_dword v181, v[28:29], off offset:56
	global_load_dword v182, v[28:29], off offset:64
	global_load_dword v183, v[28:29], off offset:72
	global_load_dword v184, v[28:29], off offset:80
	global_load_dword v185, v[28:29], off offset:88
	global_load_dword v186, v[28:29], off offset:96
	global_load_dword v187, v[28:29], off offset:104
	global_load_dword v188, v[28:29], off offset:112
	global_load_dword v189, v[28:29], off offset:120
	global_load_dword v190, v[28:29], off offset:128
	global_load_dword v191, v[28:29], off offset:136
	global_load_dword v192, v[28:29], off offset:144
	global_load_dword v193, v[28:29], off offset:152
	global_load_dword v194, v[28:29], off offset:160
	global_load_dword v195, v[28:29], off offset:168
	global_load_dword v196, v[28:29], off offset:176
	global_load_dword v197, v[28:29], off offset:184
	global_load_dword v199, v[28:29], off offset:192
	global_load_dword v200, v[28:29], off offset:200
	global_load_dword v201, v[28:29], off offset:208
	global_load_dword v202, v[28:29], off offset:216
	global_load_dword v203, v[28:29], off offset:224
	global_load_dword v204, v[28:29], off offset:232
	global_load_dword v205, v[28:29], off offset:240
	global_load_dword v206, v[28:29], off offset:248
	s_nop 0
	s_ashr_i32 s7, s6, 31
	s_waitcnt vmcnt(0) lgkmcnt(0)
	v_mul_f32_e32 v28, v59, v174
	ds_write_b32 v114, v28
	v_lshl_add_u64 v[28:29], s[6:7], 0, v[2:3]
	v_lshl_add_u64 v[28:29], v[28:29], 2, s[48:49]
	s_nop 0
	s_waitcnt vmcnt(0) lgkmcnt(0)
	v_mul_f32_e32 v28, v60, v175
	s_cbranch_execnz .LBB0_1236

.LBB0_1236:
	v_add_u32_e32 v29, v1, v120
	ds_write_b32 v29, v28
	v_cndmask_b32_e64 v28, 0, 1, s[24:25]
	v_cmp_ne_u32_e64 s[0:1], 1, v28
	s_andn2_b64 vcc, exec, s[24:25]
	v_add_u32_e32 v28, v1, v121
	s_cbranch_vccnz .LBB0_1281
	s_ashr_i32 s7, s6, 31
	s_waitcnt vmcnt(0)
	v_lshl_add_u64 v[60:61], s[6:7], 0, v[2:3]
	v_lshl_add_u64 v[60:61], v[60:61], 2, s[48:49]
	s_nop 0
	s_waitcnt vmcnt(0) lgkmcnt(0)
	v_mul_f32_e32 v29, v57, v176
	ds_write_b32 v28, v29
	s_nop 0
	s_waitcnt vmcnt(0) lgkmcnt(0)
	v_mul_f32_e32 v29, v58, v177
	s_cbranch_execnz .LBB0_1239

.LBB0_1239:
	v_add_u32_e32 v28, v1, v122
	ds_write_b32 v28, v29
	s_and_b64 vcc, exec, s[0:1]
	v_add_u32_e32 v28, v1, v123
	s_cbranch_vccnz .LBB0_1282
	s_ashr_i32 s7, s6, 31
	s_waitcnt vmcnt(0)
	v_lshl_add_u64 v[58:59], s[6:7], 0, v[2:3]
	v_lshl_add_u64 v[58:59], v[58:59], 2, s[48:49]
	s_nop 0
	s_waitcnt vmcnt(0) lgkmcnt(0)
	v_mul_f32_e32 v29, v55, v178
	ds_write_b32 v28, v29
	s_nop 0
	s_waitcnt vmcnt(0) lgkmcnt(0)
	v_mul_f32_e32 v29, v56, v179
	s_cbranch_execnz .LBB0_1242

.LBB0_1242:
	v_add_u32_e32 v28, v1, v124
	ds_write_b32 v28, v29
	s_and_b64 vcc, exec, s[0:1]
	v_add_u32_e32 v28, v1, v125
	s_cbranch_vccnz .LBB0_1283
	s_ashr_i32 s7, s6, 31
	s_waitcnt vmcnt(0)
	v_lshl_add_u64 v[56:57], s[6:7], 0, v[2:3]
	v_lshl_add_u64 v[56:57], v[56:57], 2, s[48:49]
	s_nop 0
	s_waitcnt vmcnt(0) lgkmcnt(0)
	v_mul_f32_e32 v29, v53, v180
	ds_write_b32 v28, v29
	s_nop 0
	s_waitcnt vmcnt(0) lgkmcnt(0)
	v_mul_f32_e32 v29, v54, v181
	s_cbranch_execnz .LBB0_1245

.LBB0_1245:
	v_add_u32_e32 v28, v1, v126
	ds_write_b32 v28, v29
	s_and_b64 vcc, exec, s[0:1]
	v_add_u32_e32 v28, v1, v127
	s_cbranch_vccnz .LBB0_1284
	s_ashr_i32 s7, s6, 31
	s_waitcnt vmcnt(0)
	v_lshl_add_u64 v[54:55], s[6:7], 0, v[2:3]
	v_lshl_add_u64 v[54:55], v[54:55], 2, s[48:49]
	s_nop 0
	s_waitcnt vmcnt(0) lgkmcnt(0)
	v_mul_f32_e32 v29, v51, v182
	ds_write_b32 v28, v29
	s_nop 0
	s_waitcnt vmcnt(0) lgkmcnt(0)
	v_mul_f32_e32 v29, v52, v183
	s_cbranch_execnz .LBB0_1248

.LBB0_1248:
	v_add_u32_e32 v28, v1, v128
	ds_write_b32 v28, v29
	s_and_b64 vcc, exec, s[0:1]
	v_add_u32_e32 v28, v1, v129
	s_cbranch_vccnz .LBB0_1285
	s_ashr_i32 s7, s6, 31
	s_waitcnt vmcnt(0)
	v_lshl_add_u64 v[52:53], s[6:7], 0, v[2:3]
	v_lshl_add_u64 v[52:53], v[52:53], 2, s[48:49]
	s_nop 0
	s_waitcnt vmcnt(0) lgkmcnt(0)
	v_mul_f32_e32 v29, v49, v184
	ds_write_b32 v28, v29
	s_nop 0
	s_waitcnt vmcnt(0) lgkmcnt(0)
	v_mul_f32_e32 v29, v50, v185
	s_cbranch_execnz .LBB0_1251

.LBB0_1251:
	v_add_u32_e32 v28, v1, v130
	ds_write_b32 v28, v29
	s_and_b64 vcc, exec, s[0:1]
	v_add_u32_e32 v28, v1, v131
	s_cbranch_vccnz .LBB0_1286
	s_ashr_i32 s7, s6, 31
	s_waitcnt vmcnt(0)
	v_lshl_add_u64 v[50:51], s[6:7], 0, v[2:3]
	v_lshl_add_u64 v[50:51], v[50:51], 2, s[48:49]
	s_nop 0
	s_waitcnt vmcnt(0) lgkmcnt(0)
	v_mul_f32_e32 v29, v47, v186
	ds_write_b32 v28, v29
	s_nop 0
	s_waitcnt vmcnt(0) lgkmcnt(0)
	v_mul_f32_e32 v29, v48, v187
	s_cbranch_execnz .LBB0_1254

.LBB0_1254:
	v_add_u32_e32 v28, v1, v132
	ds_write_b32 v28, v29
	s_and_b64 vcc, exec, s[0:1]
	v_add_u32_e32 v28, v1, v133
	s_cbranch_vccnz .LBB0_1287
	s_ashr_i32 s7, s6, 31
	s_waitcnt vmcnt(0)
	v_lshl_add_u64 v[48:49], s[6:7], 0, v[2:3]
	v_lshl_add_u64 v[48:49], v[48:49], 2, s[48:49]
	s_nop 0
	s_waitcnt vmcnt(0) lgkmcnt(0)
	v_mul_f32_e32 v29, v45, v188
	ds_write_b32 v28, v29
	s_nop 0
	s_waitcnt vmcnt(0) lgkmcnt(0)
	v_mul_f32_e32 v29, v46, v189
	s_cbranch_execnz .LBB0_1257

.LBB0_1257:
	v_add_u32_e32 v28, v1, v134
	ds_write_b32 v28, v29
	s_and_b64 vcc, exec, s[0:1]
	v_add_u32_e32 v28, v1, v135
	s_cbranch_vccnz .LBB0_1288
	s_ashr_i32 s7, s6, 31
	s_waitcnt vmcnt(0)
	v_lshl_add_u64 v[46:47], s[6:7], 0, v[2:3]
	v_lshl_add_u64 v[46:47], v[46:47], 2, s[48:49]
	s_nop 0
	s_waitcnt vmcnt(0) lgkmcnt(0)
	v_mul_f32_e32 v29, v43, v190
	ds_write_b32 v28, v29
	s_nop 0
	s_waitcnt vmcnt(0) lgkmcnt(0)
	v_mul_f32_e32 v29, v44, v191
	s_cbranch_execnz .LBB0_1260

.LBB0_1260:
	v_add_u32_e32 v28, v1, v136
	ds_write_b32 v28, v29
	s_and_b64 vcc, exec, s[0:1]
	v_add_u32_e32 v28, v1, v137
	s_cbranch_vccnz .LBB0_1289
	s_ashr_i32 s7, s6, 31
	s_waitcnt vmcnt(0)
	v_lshl_add_u64 v[44:45], s[6:7], 0, v[2:3]
	v_lshl_add_u64 v[44:45], v[44:45], 2, s[48:49]
	s_nop 0
	s_waitcnt vmcnt(0) lgkmcnt(0)
	v_mul_f32_e32 v29, v41, v192
	ds_write_b32 v28, v29
	s_nop 0
	s_waitcnt vmcnt(0) lgkmcnt(0)
	v_mul_f32_e32 v29, v42, v193
	s_cbranch_execnz .LBB0_1263

.LBB0_1263:
	v_add_u32_e32 v28, v1, v138
	ds_write_b32 v28, v29
	s_and_b64 vcc, exec, s[0:1]
	v_add_u32_e32 v28, v1, v139
	s_cbranch_vccnz .LBB0_1290
	s_ashr_i32 s7, s6, 31
	s_waitcnt vmcnt(0)
	v_lshl_add_u64 v[42:43], s[6:7], 0, v[2:3]
	v_lshl_add_u64 v[42:43], v[42:43], 2, s[48:49]
	s_nop 0
	s_waitcnt vmcnt(0) lgkmcnt(0)
	v_mul_f32_e32 v29, v39, v194
	ds_write_b32 v28, v29
	s_nop 0
	s_waitcnt vmcnt(0) lgkmcnt(0)
	v_mul_f32_e32 v29, v40, v195
	s_cbranch_execnz .LBB0_1266

.LBB0_1266:
	v_add_u32_e32 v28, v1, v140
	ds_write_b32 v28, v29
	s_and_b64 vcc, exec, s[0:1]
	v_add_u32_e32 v28, v1, v141
	s_cbranch_vccnz .LBB0_1291
	s_ashr_i32 s7, s6, 31
	s_waitcnt vmcnt(0)
	v_lshl_add_u64 v[40:41], s[6:7], 0, v[2:3]
	v_lshl_add_u64 v[40:41], v[40:41], 2, s[48:49]
	s_nop 0
	s_waitcnt vmcnt(0) lgkmcnt(0)
	v_mul_f32_e32 v29, v37, v196
	ds_write_b32 v28, v29
	s_nop 0
	s_waitcnt vmcnt(0) lgkmcnt(0)
	v_mul_f32_e32 v29, v38, v197
	s_cbranch_execnz .LBB0_1269

.LBB0_1269:
	v_add_u32_e32 v28, v1, v142
	ds_write_b32 v28, v29
	s_and_b64 vcc, exec, s[0:1]
	v_add_u32_e32 v28, v1, v143
	s_cbranch_vccnz .LBB0_1292
	s_ashr_i32 s7, s6, 31
	s_waitcnt vmcnt(0)
	v_lshl_add_u64 v[38:39], s[6:7], 0, v[2:3]
	v_lshl_add_u64 v[38:39], v[38:39], 2, s[48:49]
	s_nop 0
	s_waitcnt vmcnt(0) lgkmcnt(0)
	v_mul_f32_e32 v29, v35, v199
	ds_write_b32 v28, v29
	s_nop 0
	s_waitcnt vmcnt(0) lgkmcnt(0)
	v_mul_f32_e32 v29, v36, v200
	s_cbranch_execnz .LBB0_1272

.LBB0_1272:
	v_add_u32_e32 v28, v1, v144
	s_and_b64 vcc, exec, s[0:1]
	ds_write_b32 v28, v29
	s_cbranch_vccnz .LBB0_1293
	s_ashr_i32 s7, s6, 31
	s_waitcnt vmcnt(0)
	v_lshl_add_u64 v[36:37], s[6:7], 0, v[2:3]
	v_lshl_add_u64 v[36:37], v[36:37], 2, s[48:49]
	s_nop 0
	s_waitcnt vmcnt(0) lgkmcnt(0)
	v_mul_f32_e32 v29, v33, v201
	ds_write_b32 v28, v29 offset:264
	s_nop 0
	s_waitcnt vmcnt(0) lgkmcnt(0)
	v_mul_f32_e32 v29, v34, v202
	s_cbranch_execnz .LBB0_1275

.LBB0_1275:
	s_and_b64 vcc, exec, s[0:1]
	ds_write_b32 v28, v29 offset:528
	s_cbranch_vccnz .LBB0_1294
	s_ashr_i32 s7, s6, 31
	s_waitcnt vmcnt(0)
	v_lshl_add_u64 v[34:35], s[6:7], 0, v[2:3]
	v_lshl_add_u64 v[34:35], v[34:35], 2, s[48:49]
	s_nop 0
	s_waitcnt vmcnt(0) lgkmcnt(0)
	v_mul_f32_e32 v29, v31, v203
	ds_write_b32 v28, v29 offset:792
	s_nop 0
	s_waitcnt vmcnt(0) lgkmcnt(0)
	v_mul_f32_e32 v29, v32, v204
	s_cbranch_execnz .LBB0_1278

.LBB0_1278:
	s_and_b64 vcc, exec, s[0:1]
	ds_write_b32 v28, v29 offset:1056
	s_cbranch_vccnz .LBB0_1295
	s_ashr_i32 s7, s6, 31
	s_waitcnt vmcnt(0)
	v_lshl_add_u64 v[32:33], s[6:7], 0, v[2:3]
	v_lshl_add_u64 v[32:33], v[32:33], 2, s[48:49]
	s_nop 0
	s_waitcnt vmcnt(0) lgkmcnt(0)
	v_mul_f32_e32 v29, v30, v205
	ds_write_b32 v28, v29 offset:1320
	s_nop 0
	s_waitcnt vmcnt(0) lgkmcnt(0)
	v_mul_f32_e32 v29, v25, v206
	s_cbranch_execnz .LBB0_1037
	s_branch .LBB0_1296
